# sgemm_sample: five staging register sets (four K slabs in flight)
# speedup vs baseline: 1.0321x; 1.0011x over previous
; template <int MODE>
; __device__ __forceinline__ void sgemm_sample(LAS unsigned char* lds, const bf16_t* A, const bf16_t* Bt, int K, const float* resid, float* out, bf16_t* xb, float* ssq_out, const float* ssq_in) {
;     ...
;     for (int uu = u; uu < 2048; uu += gridDim.x * 8) {
;         const int rt = uu >> 6, ct = uu & 63; const int row = NTOKP + rt * 16 + fr, col0 = ct * 16 + fq * 4;
;         const bf16_t* ap = A + (size_t)row * K + fq * 8; const bf16_t* bp = Bt + (size_t)(ct * 16 + fr) * K + fq * 8;
;         f32x4 acc = {0.f, 0.f, 0.f, 0.f};
; #pragma unroll 8
;         for (int ks = 0; ks < K / 32; ++ks) {
;             const bf16x8 a = *(const bf16x8*)(ap + ks * 32); const bf16x8 b = *(const bf16x8*)(bp + ks * 32);
;             acc = __builtin_amdgcn_mfma_f32_16x16x32_bf16(b, a, acc, 0, 0, 0);
;         }
;     ...
;             const f32x4 x = *(const f32x4*)(resid + (size_t)(row - NTOKP) * D + col0) + acc;
.LBB0_894:
	s_and_b32 s6, s15, 63
	v_lshl_or_b32 v4, s6, 15, v21
	s_ashr_i32 s6, s3, 2
	s_and_b32 s6, s6, -16
	s_add_i32 s6, s6, 0x8000
	v_or_b32_e32 v12, s6, v17
	v_ashrrev_i32_e32 v13, 31, v12
	v_lshlrev_b64 v[8:9], 11, v[12:13]
	v_lshl_add_u64 v[10:11], v[6:7], 0, v[4:5]
	v_lshl_add_u64 v[14:15], v[6:7], 0, v[8:9]
	s_mov_b64 s[16:17], 0
	v_mov_b32_e32 v0, 0
	v_mov_b32_e32 v1, v5
	v_mov_b32_e32 v2, v5
	v_mov_b32_e32 v3, v5
	s_cmpk_lg_i32 s34, 0x100
	s_cbranch_scc1 .LBB0_895
	s_waitcnt vmcnt(0)
	s_and_b32 s18, s3, 63
	v_lshl_or_b32 v24, s18, 4, v18
	v_lshlrev_b64 v[14:15], 12, v[12:13]
	v_lshl_add_u64 v[10:11], s[40:41], 0, v[14:15]
	v_lshlrev_b32_e32 v4, 2, v24
	v_lshl_add_u64 v[10:11], v[10:11], 0, v[4:5]
	v_add_co_u32_e32 v10, vcc, 0xf8000000, v10
	v_lshl_add_u64 v[14:15], s[90:91], 0, v[14:15]
	s_nop 0
	v_addc_co_u32_e32 v11, vcc, -1, v11, vcc
	global_load_dwordx4 v[10:13], v[10:11], off
	s_lshr_b32 s100, s2, 3
	s_lshl_b32 s100, s100, 4
	s_add_i32 s100, s100, 0x8000
	s_mul_i32 s100, s100, 0x800
	s_add_u32 s96, s92, s100
	s_addc_u32 s97, s93, 0
	s_add_u32 s96, s96, 0x15780000
	s_addc_u32 s97, s97, 0
	s_and_b32 s100, s2, 7
	s_lshl_b32 s100, s100, 7
	s_mul_i32 s100, s100, 0x800
	s_add_u32 s98, s92, s100
	s_addc_u32 s99, s93, 0
	s_add_u32 s98, s98, 0x840000
	s_addc_u32 s99, s99, 0
	v_lshrrev_b32_e32 v179, 4, v200
	v_and_b32_e32 v180, 15, v200
	v_and_b32_e32 v181, 15, v179
	v_xor_b32_e32 v180, v180, v181
	v_lshlrev_b32_e32 v180, 4, v180
	s_mov_b32 s100, 0x800
	v_mad_u32_u24 v164, v179, s100, v180
	v_add_u32_e32 v165, 0x10000, v164
	v_add_u32_e32 v166, 0x20000, v164
	v_add_u32_e32 v167, 0x30000, v164
	v_mad_u32_u24 v168, v181, s100, v180
	v_lshlrev_b32_e32 v169, 4, v200
	v_add_u32_e32 v169, 1024, v169
	v_and_b32_e32 v170, 0xff, v200
	v_lshlrev_b32_e32 v170, 4, v170
	v_add_u32_e32 v170, 33792, v170
	v_and_b32_e32 v179, 15, v200
	v_bfe_u32 v180, v200, 4, 2
	v_and_b32_e32 v181, 3, v179
	v_xor_b32_e32 v180, v180, v181
	v_lshlrev_b32_e32 v180, 4, v180
	v_lshrrev_b32_e32 v181, 2, v179
	v_lshl_add_u32 v180, v181, 6, v180
	v_lshl_add_u32 v180, v179, 8, v180
	v_add_u32_e32 v171, 33792, v180
	v_lshrrev_b32_e32 v181, 6, v200
	v_lshlrev_b32_e32 v181, 12, v181
	v_add_u32_e32 v175, v180, v181
	v_add_u32_e32 v175, 1024, v175
	v_xor_b32_e32 v172, 0x40, v171
	v_xor_b32_e32 v176, 0x40, v175
	v_xor_b32_e32 v173, 0x80, v171
	v_xor_b32_e32 v177, 0x80, v175
	v_xor_b32_e32 v174, 0xc0, v171
	v_xor_b32_e32 v178, 0xc0, v175
	global_load_dwordx4 v[64:67], v164, s[98:99]
	global_load_dwordx4 v[68:71], v165, s[98:99]
	global_load_dwordx4 v[72:75], v166, s[98:99]
	global_load_dwordx4 v[76:79], v167, s[98:99]
	global_load_dwordx4 v[80:83], v168, s[96:97]
	s_add_u32 s98, s98, 0x100
	s_addc_u32 s99, s99, 0
	s_add_u32 s96, s96, 0x100
	s_addc_u32 s97, s97, 0
	global_load_dwordx4 v[84:87], v164, s[98:99]
	global_load_dwordx4 v[88:91], v165, s[98:99]
	global_load_dwordx4 v[92:95], v166, s[98:99]
	global_load_dwordx4 v[96:99], v167, s[98:99]
	global_load_dwordx4 v[100:103], v168, s[96:97]
	s_add_u32 s98, s98, 0x100
	s_addc_u32 s99, s99, 0
	s_add_u32 s96, s96, 0x100
	s_addc_u32 s97, s97, 0
	global_load_dwordx4 v[104:107], v164, s[98:99]
	global_load_dwordx4 v[108:111], v165, s[98:99]
	global_load_dwordx4 v[112:115], v166, s[98:99]
	global_load_dwordx4 v[116:119], v167, s[98:99]
	global_load_dwordx4 v[120:123], v168, s[96:97]
	s_add_u32 s98, s98, 0x100
	s_addc_u32 s99, s99, 0
	s_add_u32 s96, s96, 0x100
	s_addc_u32 s97, s97, 0
	global_load_dwordx4 v[124:127], v164, s[98:99]
	global_load_dwordx4 v[128:131], v165, s[98:99]
	global_load_dwordx4 v[132:135], v166, s[98:99]
	global_load_dwordx4 v[136:139], v167, s[98:99]
	global_load_dwordx4 v[140:143], v168, s[96:97]
	s_add_u32 s98, s98, 0x100
	s_addc_u32 s99, s99, 0
	s_add_u32 s96, s96, 0x100
	s_addc_u32 s97, s97, 0
	global_load_dwordx4 v[144:147], v164, s[98:99]
	global_load_dwordx4 v[148:151], v165, s[98:99]
	global_load_dwordx4 v[152:155], v166, s[98:99]
	global_load_dwordx4 v[156:159], v167, s[98:99]
	global_load_dwordx4 v[160:163], v168, s[96:97]
	s_add_u32 s98, s98, 0x100
	s_addc_u32 s99, s99, 0
	s_add_u32 s96, s96, 0x100
	s_addc_u32 s97, s97, 0
	s_waitcnt vmcnt(24)
	ds_write_b128 v169, v[64:67]
	s_waitcnt vmcnt(23)
	ds_write_b128 v169, v[68:71] offset:8192
	s_waitcnt vmcnt(22)
	ds_write_b128 v169, v[72:75] offset:16384
	s_waitcnt vmcnt(21)
	ds_write_b128 v169, v[76:79] offset:24576
	s_waitcnt vmcnt(20)
	ds_write_b128 v170, v[80:83]
	s_waitcnt lgkmcnt(0)
	s_barrier
	s_waitcnt vmcnt(19)
	ds_write_b128 v169, v[84:87] offset:36864
	s_waitcnt vmcnt(18)
	ds_write_b128 v169, v[88:91] offset:45056
	s_waitcnt vmcnt(17)
	ds_write_b128 v169, v[92:95] offset:53248
	s_waitcnt vmcnt(16)
	ds_write_b128 v169, v[96:99] offset:61440
	s_waitcnt vmcnt(15)
	ds_write_b128 v170, v[100:103] offset:36864
	global_load_dwordx4 v[64:67], v164, s[98:99]
	global_load_dwordx4 v[68:71], v165, s[98:99]
	global_load_dwordx4 v[72:75], v166, s[98:99]
	global_load_dwordx4 v[76:79], v167, s[98:99]
	global_load_dwordx4 v[80:83], v168, s[96:97]
	s_add_u32 s98, s98, 0x100
	s_addc_u32 s99, s99, 0
	s_add_u32 s96, s96, 0x100
	s_addc_u32 s97, s97, 0
	ds_read_b128 v[204:207], v175
	ds_read_b128 v[208:211], v171
	ds_read_b128 v[212:215], v176
	ds_read_b128 v[216:219], v172
	ds_read_b128 v[220:223], v177
	ds_read_b128 v[224:227], v173
	ds_read_b128 v[228:231], v178
	ds_read_b128 v[232:235], v174
	s_waitcnt lgkmcnt(6)
	v_mfma_f32_16x16x32_bf16 v[0:3], v[204:207], v[208:211], v[0:3]
	s_waitcnt lgkmcnt(4)
	v_mfma_f32_16x16x32_bf16 v[0:3], v[212:215], v[216:219], v[0:3]
	s_waitcnt lgkmcnt(2)
	v_mfma_f32_16x16x32_bf16 v[0:3], v[220:223], v[224:227], v[0:3]
	s_waitcnt lgkmcnt(0)
	v_mfma_f32_16x16x32_bf16 v[0:3], v[228:231], v[232:235], v[0:3]
	s_waitcnt lgkmcnt(0)
	s_barrier
; template <int MODE>
; __device__ __forceinline__ void sgemm_sample(LAS unsigned char* lds, const bf16_t* A, const bf16_t* Bt, int K, const float* resid, float* out, bf16_t* xb, float* ssq_out, const float* ssq_in) {
;     ...
; #pragma unroll 8
;         for (int ks = 0; ks < K / 32; ++ks) {
;             const bf16x8 a = *(const bf16x8*)(ap + ks * 32); const bf16x8 b = *(const bf16x8*)(bp + ks * 32);
;             acc = __builtin_amdgcn_mfma_f32_16x16x32_bf16(b, a, acc, 0, 0, 0);
;         }
	s_waitcnt vmcnt(19)
	ds_write_b128 v169, v[104:107]
	s_waitcnt vmcnt(18)
	ds_write_b128 v169, v[108:111] offset:8192
	s_waitcnt vmcnt(17)
	ds_write_b128 v169, v[112:115] offset:16384
	s_waitcnt vmcnt(16)
	ds_write_b128 v169, v[116:119] offset:24576
	s_waitcnt vmcnt(15)
	ds_write_b128 v170, v[120:123]
	global_load_dwordx4 v[84:87], v164, s[98:99]
	global_load_dwordx4 v[88:91], v165, s[98:99]
	global_load_dwordx4 v[92:95], v166, s[98:99]
	global_load_dwordx4 v[96:99], v167, s[98:99]
	global_load_dwordx4 v[100:103], v168, s[96:97]
	s_add_u32 s98, s98, 0x100
	s_addc_u32 s99, s99, 0
	s_add_u32 s96, s96, 0x100
	s_addc_u32 s97, s97, 0
	ds_read_b128 v[204:207], v175 offset:36864
	ds_read_b128 v[208:211], v171 offset:36864
	ds_read_b128 v[212:215], v176 offset:36864
	ds_read_b128 v[216:219], v172 offset:36864
	ds_read_b128 v[220:223], v177 offset:36864
	ds_read_b128 v[224:227], v173 offset:36864
	ds_read_b128 v[228:231], v178 offset:36864
	ds_read_b128 v[232:235], v174 offset:36864
	s_waitcnt lgkmcnt(6)
	v_mfma_f32_16x16x32_bf16 v[0:3], v[204:207], v[208:211], v[0:3]
	s_waitcnt lgkmcnt(4)
	v_mfma_f32_16x16x32_bf16 v[0:3], v[212:215], v[216:219], v[0:3]
	s_waitcnt lgkmcnt(2)
	v_mfma_f32_16x16x32_bf16 v[0:3], v[220:223], v[224:227], v[0:3]
	s_waitcnt lgkmcnt(0)
	v_mfma_f32_16x16x32_bf16 v[0:3], v[228:231], v[232:235], v[0:3]
	s_waitcnt lgkmcnt(0)
	s_barrier
	s_waitcnt vmcnt(19)
	ds_write_b128 v169, v[124:127] offset:36864
	s_waitcnt vmcnt(18)
	ds_write_b128 v169, v[128:131] offset:45056
	s_waitcnt vmcnt(17)
	ds_write_b128 v169, v[132:135] offset:53248
	s_waitcnt vmcnt(16)
	ds_write_b128 v169, v[136:139] offset:61440
	s_waitcnt vmcnt(15)
	ds_write_b128 v170, v[140:143] offset:36864
	global_load_dwordx4 v[104:107], v164, s[98:99]
	global_load_dwordx4 v[108:111], v165, s[98:99]
	global_load_dwordx4 v[112:115], v166, s[98:99]
	global_load_dwordx4 v[116:119], v167, s[98:99]
	global_load_dwordx4 v[120:123], v168, s[96:97]
	s_add_u32 s98, s98, 0x100
	s_addc_u32 s99, s99, 0
	s_add_u32 s96, s96, 0x100
	s_addc_u32 s97, s97, 0
	ds_read_b128 v[204:207], v175
	ds_read_b128 v[208:211], v171
	ds_read_b128 v[212:215], v176
	ds_read_b128 v[216:219], v172
	ds_read_b128 v[220:223], v177
	ds_read_b128 v[224:227], v173
	ds_read_b128 v[228:231], v178
	ds_read_b128 v[232:235], v174
	s_waitcnt lgkmcnt(6)
	v_mfma_f32_16x16x32_bf16 v[0:3], v[204:207], v[208:211], v[0:3]
	s_waitcnt lgkmcnt(4)
	v_mfma_f32_16x16x32_bf16 v[0:3], v[212:215], v[216:219], v[0:3]
	s_waitcnt lgkmcnt(2)
	v_mfma_f32_16x16x32_bf16 v[0:3], v[220:223], v[224:227], v[0:3]
	s_waitcnt lgkmcnt(0)
	v_mfma_f32_16x16x32_bf16 v[0:3], v[228:231], v[232:235], v[0:3]
	s_waitcnt lgkmcnt(0)
	s_barrier
	s_waitcnt vmcnt(19)
	ds_write_b128 v169, v[144:147]
	s_waitcnt vmcnt(18)
	ds_write_b128 v169, v[148:151] offset:8192
	s_waitcnt vmcnt(17)
	ds_write_b128 v169, v[152:155] offset:16384
	s_waitcnt vmcnt(16)
	ds_write_b128 v169, v[156:159] offset:24576
	s_waitcnt vmcnt(15)
	ds_write_b128 v170, v[160:163]
	ds_read_b128 v[204:207], v175 offset:36864
	ds_read_b128 v[208:211], v171 offset:36864
	ds_read_b128 v[212:215], v176 offset:36864
	ds_read_b128 v[216:219], v172 offset:36864
	ds_read_b128 v[220:223], v177 offset:36864
	ds_read_b128 v[224:227], v173 offset:36864
	ds_read_b128 v[228:231], v178 offset:36864
	ds_read_b128 v[232:235], v174 offset:36864
	s_waitcnt lgkmcnt(6)
	v_mfma_f32_16x16x32_bf16 v[0:3], v[204:207], v[208:211], v[0:3]
	s_waitcnt lgkmcnt(4)
	v_mfma_f32_16x16x32_bf16 v[0:3], v[212:215], v[216:219], v[0:3]
	s_waitcnt lgkmcnt(2)
	v_mfma_f32_16x16x32_bf16 v[0:3], v[220:223], v[224:227], v[0:3]
	s_waitcnt lgkmcnt(0)
	v_mfma_f32_16x16x32_bf16 v[0:3], v[228:231], v[232:235], v[0:3]
	s_waitcnt lgkmcnt(0)
	s_barrier
; template <int MODE>
; __device__ __forceinline__ void sgemm_sample(LAS unsigned char* lds, const bf16_t* A, const bf16_t* Bt, int K, const float* resid, float* out, bf16_t* xb, float* ssq_out, const float* ssq_in) {
;     ...
; #pragma unroll 8
;         for (int ks = 0; ks < K / 32; ++ks) {
;             const bf16x8 a = *(const bf16x8*)(ap + ks * 32); const bf16x8 b = *(const bf16x8*)(bp + ks * 32);
;             acc = __builtin_amdgcn_mfma_f32_16x16x32_bf16(b, a, acc, 0, 0, 0);
;         }
	s_waitcnt vmcnt(14)
	ds_write_b128 v169, v[64:67] offset:36864
	s_waitcnt vmcnt(13)
	ds_write_b128 v169, v[68:71] offset:45056
	s_waitcnt vmcnt(12)
	ds_write_b128 v169, v[72:75] offset:53248
	s_waitcnt vmcnt(11)
	ds_write_b128 v169, v[76:79] offset:61440
	s_waitcnt vmcnt(10)
	ds_write_b128 v170, v[80:83] offset:36864
	ds_read_b128 v[204:207], v175
	ds_read_b128 v[208:211], v171
	ds_read_b128 v[212:215], v176
	ds_read_b128 v[216:219], v172
	ds_read_b128 v[220:223], v177
	ds_read_b128 v[224:227], v173
	ds_read_b128 v[228:231], v178
	ds_read_b128 v[232:235], v174
	s_waitcnt lgkmcnt(6)
	v_mfma_f32_16x16x32_bf16 v[0:3], v[204:207], v[208:211], v[0:3]
	s_waitcnt lgkmcnt(4)
	v_mfma_f32_16x16x32_bf16 v[0:3], v[212:215], v[216:219], v[0:3]
	s_waitcnt lgkmcnt(2)
	v_mfma_f32_16x16x32_bf16 v[0:3], v[220:223], v[224:227], v[0:3]
	s_waitcnt lgkmcnt(0)
	v_mfma_f32_16x16x32_bf16 v[0:3], v[228:231], v[232:235], v[0:3]
	s_waitcnt lgkmcnt(0)
	s_barrier
	s_waitcnt vmcnt(9)
	ds_write_b128 v169, v[84:87]
	s_waitcnt vmcnt(8)
	ds_write_b128 v169, v[88:91] offset:8192
	s_waitcnt vmcnt(7)
	ds_write_b128 v169, v[92:95] offset:16384
	s_waitcnt vmcnt(6)
	ds_write_b128 v169, v[96:99] offset:24576
	s_waitcnt vmcnt(5)
	ds_write_b128 v170, v[100:103]
	ds_read_b128 v[204:207], v175 offset:36864
	ds_read_b128 v[208:211], v171 offset:36864
	ds_read_b128 v[212:215], v176 offset:36864
	ds_read_b128 v[216:219], v172 offset:36864
	ds_read_b128 v[220:223], v177 offset:36864
	ds_read_b128 v[224:227], v173 offset:36864
	ds_read_b128 v[228:231], v178 offset:36864
	ds_read_b128 v[232:235], v174 offset:36864
	s_waitcnt lgkmcnt(6)
	v_mfma_f32_16x16x32_bf16 v[0:3], v[204:207], v[208:211], v[0:3]
	s_waitcnt lgkmcnt(4)
	v_mfma_f32_16x16x32_bf16 v[0:3], v[212:215], v[216:219], v[0:3]
	s_waitcnt lgkmcnt(2)
	v_mfma_f32_16x16x32_bf16 v[0:3], v[220:223], v[224:227], v[0:3]
	s_waitcnt lgkmcnt(0)
	v_mfma_f32_16x16x32_bf16 v[0:3], v[228:231], v[232:235], v[0:3]
	s_waitcnt lgkmcnt(0)
	s_barrier
	s_waitcnt vmcnt(4)
	ds_write_b128 v169, v[104:107] offset:36864
	s_waitcnt vmcnt(3)
	ds_write_b128 v169, v[108:111] offset:45056
	s_waitcnt vmcnt(2)
	ds_write_b128 v169, v[112:115] offset:53248
	s_waitcnt vmcnt(1)
	ds_write_b128 v169, v[116:119] offset:61440
	s_waitcnt vmcnt(0)
	ds_write_b128 v170, v[120:123] offset:36864
	ds_read_b128 v[204:207], v175
	ds_read_b128 v[208:211], v171
	ds_read_b128 v[212:215], v176
	ds_read_b128 v[216:219], v172
	ds_read_b128 v[220:223], v177
	ds_read_b128 v[224:227], v173
	ds_read_b128 v[228:231], v178
	ds_read_b128 v[232:235], v174
	s_waitcnt lgkmcnt(6)
	v_mfma_f32_16x16x32_bf16 v[0:3], v[204:207], v[208:211], v[0:3]
	s_waitcnt lgkmcnt(4)
	v_mfma_f32_16x16x32_bf16 v[0:3], v[212:215], v[216:219], v[0:3]
	s_waitcnt lgkmcnt(2)
	v_mfma_f32_16x16x32_bf16 v[0:3], v[220:223], v[224:227], v[0:3]
	s_waitcnt lgkmcnt(0)
	v_mfma_f32_16x16x32_bf16 v[0:3], v[228:231], v[232:235], v[0:3]
	s_waitcnt lgkmcnt(0)
	s_barrier
	ds_read_b128 v[204:207], v175 offset:36864
	ds_read_b128 v[208:211], v171 offset:36864
	ds_read_b128 v[212:215], v176 offset:36864
	ds_read_b128 v[216:219], v172 offset:36864
	ds_read_b128 v[220:223], v177 offset:36864
	ds_read_b128 v[224:227], v173 offset:36864
	ds_read_b128 v[228:231], v178 offset:36864
	ds_read_b128 v[232:235], v174 offset:36864
	s_waitcnt lgkmcnt(6)
	v_mfma_f32_16x16x32_bf16 v[0:3], v[204:207], v[208:211], v[0:3]
	s_waitcnt lgkmcnt(4)
	v_mfma_f32_16x16x32_bf16 v[0:3], v[212:215], v[216:219], v[0:3]
	s_waitcnt lgkmcnt(2)
	v_mfma_f32_16x16x32_bf16 v[0:3], v[220:223], v[224:227], v[0:3]
	s_waitcnt lgkmcnt(0)
	v_mfma_f32_16x16x32_bf16 v[0:3], v[228:231], v[232:235], v[0:3]
	s_nop 7
	s_branch .Lsgx0_done

; template <int MODE>
; __device__ __forceinline__ void sgemm_sample(LAS unsigned char* lds, const bf16_t* A, const bf16_t* Bt, int K, const float* resid, float* out, bf16_t* xb, float* ssq_out, const float* ssq_in) {
;     ...
;     for (int uu = u; uu < 2048; uu += gridDim.x * 8) {
;         const int rt = uu >> 6, ct = uu & 63; const int row = NTOKP + rt * 16 + fr, col0 = ct * 16 + fq * 4;
;         const bf16_t* ap = A + (size_t)row * K + fq * 8; const bf16_t* bp = Bt + (size_t)(ct * 16 + fr) * K + fq * 8;
;         f32x4 acc = {0.f, 0.f, 0.f, 0.f};
; #pragma unroll 8
;         for (int ks = 0; ks < K / 32; ++ks) {
;             const bf16x8 a = *(const bf16x8*)(ap + ks * 32); const bf16x8 b = *(const bf16x8*)(bp + ks * 32);
;             acc = __builtin_amdgcn_mfma_f32_16x16x32_bf16(b, a, acc, 0, 0, 0);
;         }
;     ...
;             const float sc = rs_from_parts(ssq_in + (size_t)row * 16) * 0.0625f;
.LBB0_999:
	s_lshl_b32 s0, s7, 11
	s_and_b32 s0, s0, 0x1f8000
	v_lshl_or_b32 v4, v18, 1, s0
	s_ashr_i32 s0, s3, 2
	s_and_b32 s0, s0, -16
	v_add_u32_e32 v10, s0, v16
	v_ashrrev_i32_e32 v11, 31, v10
	v_lshlrev_b64 v[8:9], 11, v[10:11]
	v_lshl_add_u64 v[12:13], v[6:7], 0, v[4:5]
	v_lshl_add_u64 v[14:15], v[6:7], 0, v[8:9]
	s_mov_b64 s[0:1], 0
	v_mov_b32_e32 v0, 0
	v_mov_b32_e32 v1, v5
	v_mov_b32_e32 v2, v5
	v_mov_b32_e32 v3, v5
	s_cmpk_lg_i32 s34, 0x100
	s_cbranch_scc1 .LBB0_1000
	s_waitcnt vmcnt(0)
	v_lshlrev_b64 v[10:11], 6, v[10:11]
	v_lshl_add_u64 v[14:15], s[4:5], 0, v[10:11]
	global_load_dwordx4 v[10:13], v[14:15], off
	global_load_dwordx4 v[20:23], v[14:15], off offset:16
	global_load_dwordx4 v[24:27], v[14:15], off offset:32
	global_load_dwordx4 v[28:31], v[14:15], off offset:48
	s_lshr_b32 s100, s2, 3
	s_lshl_b32 s100, s100, 4
	s_add_i32 s100, s100, 0x8000
	s_mul_i32 s100, s100, 0x800
	s_add_u32 s96, s92, s100
	s_addc_u32 s97, s93, 0
	s_add_u32 s96, s96, 0xa4c0000
	s_addc_u32 s97, s97, 0
	s_and_b32 s100, s2, 7
	s_lshl_b32 s100, s100, 7
	s_mul_i32 s100, s100, 0x800
	s_add_u32 s98, s92, s100
	s_addc_u32 s99, s93, 0
	s_add_u32 s98, s98, 0xa40000
	s_addc_u32 s99, s99, 0
	v_lshrrev_b32_e32 v179, 4, v200
	v_and_b32_e32 v180, 15, v200
	v_and_b32_e32 v181, 15, v179
	v_xor_b32_e32 v180, v180, v181
	v_lshlrev_b32_e32 v180, 4, v180
	s_mov_b32 s100, 0x800
	v_mad_u32_u24 v164, v179, s100, v180
	v_add_u32_e32 v165, 0x10000, v164
	v_add_u32_e32 v166, 0x20000, v164
	v_add_u32_e32 v167, 0x30000, v164
	v_mad_u32_u24 v168, v181, s100, v180
	v_lshlrev_b32_e32 v169, 4, v200
	v_add_u32_e32 v169, 1024, v169
	v_and_b32_e32 v170, 0xff, v200
	v_lshlrev_b32_e32 v170, 4, v170
	v_add_u32_e32 v170, 33792, v170
	v_and_b32_e32 v179, 15, v200
	v_bfe_u32 v180, v200, 4, 2
	v_and_b32_e32 v181, 3, v179
	v_xor_b32_e32 v180, v180, v181
	v_lshlrev_b32_e32 v180, 4, v180
	v_lshrrev_b32_e32 v181, 2, v179
	v_lshl_add_u32 v180, v181, 6, v180
	v_lshl_add_u32 v180, v179, 8, v180
	v_add_u32_e32 v171, 33792, v180
	v_lshrrev_b32_e32 v181, 6, v200
	v_lshlrev_b32_e32 v181, 12, v181
	v_add_u32_e32 v175, v180, v181
	v_add_u32_e32 v175, 1024, v175
	v_xor_b32_e32 v172, 0x40, v171
	v_xor_b32_e32 v176, 0x40, v175
	v_xor_b32_e32 v173, 0x80, v171
	v_xor_b32_e32 v177, 0x80, v175
	v_xor_b32_e32 v174, 0xc0, v171
	v_xor_b32_e32 v178, 0xc0, v175
	global_load_dwordx4 v[64:67], v164, s[98:99]
	global_load_dwordx4 v[68:71], v165, s[98:99]
	global_load_dwordx4 v[72:75], v166, s[98:99]
	global_load_dwordx4 v[76:79], v167, s[98:99]
	global_load_dwordx4 v[80:83], v168, s[96:97]
	s_add_u32 s98, s98, 0x100
	s_addc_u32 s99, s99, 0
	s_add_u32 s96, s96, 0x100
	s_addc_u32 s97, s97, 0
	global_load_dwordx4 v[84:87], v164, s[98:99]
	global_load_dwordx4 v[88:91], v165, s[98:99]
	global_load_dwordx4 v[92:95], v166, s[98:99]
	global_load_dwordx4 v[96:99], v167, s[98:99]
	global_load_dwordx4 v[100:103], v168, s[96:97]
	s_add_u32 s98, s98, 0x100
	s_addc_u32 s99, s99, 0
	s_add_u32 s96, s96, 0x100
	s_addc_u32 s97, s97, 0
	global_load_dwordx4 v[104:107], v164, s[98:99]
	global_load_dwordx4 v[108:111], v165, s[98:99]
	global_load_dwordx4 v[112:115], v166, s[98:99]
	global_load_dwordx4 v[116:119], v167, s[98:99]
	global_load_dwordx4 v[120:123], v168, s[96:97]
	s_add_u32 s98, s98, 0x100
	s_addc_u32 s99, s99, 0
	s_add_u32 s96, s96, 0x100
	s_addc_u32 s97, s97, 0
	global_load_dwordx4 v[124:127], v164, s[98:99]
	global_load_dwordx4 v[128:131], v165, s[98:99]
	global_load_dwordx4 v[132:135], v166, s[98:99]
	global_load_dwordx4 v[136:139], v167, s[98:99]
	global_load_dwordx4 v[140:143], v168, s[96:97]
	s_add_u32 s98, s98, 0x100
	s_addc_u32 s99, s99, 0
	s_add_u32 s96, s96, 0x100
	s_addc_u32 s97, s97, 0
	global_load_dwordx4 v[144:147], v164, s[98:99]
	global_load_dwordx4 v[148:151], v165, s[98:99]
	global_load_dwordx4 v[152:155], v166, s[98:99]
	global_load_dwordx4 v[156:159], v167, s[98:99]
	global_load_dwordx4 v[160:163], v168, s[96:97]
	s_add_u32 s98, s98, 0x100
	s_addc_u32 s99, s99, 0
	s_add_u32 s96, s96, 0x100
	s_addc_u32 s97, s97, 0
	s_waitcnt vmcnt(24)
	ds_write_b128 v169, v[64:67]
	s_waitcnt vmcnt(23)
	ds_write_b128 v169, v[68:71] offset:8192
	s_waitcnt vmcnt(22)
	ds_write_b128 v169, v[72:75] offset:16384
	s_waitcnt vmcnt(21)
	ds_write_b128 v169, v[76:79] offset:24576
	s_waitcnt vmcnt(20)
	ds_write_b128 v170, v[80:83]
	s_waitcnt lgkmcnt(0)
	s_barrier
	s_waitcnt vmcnt(19)
	ds_write_b128 v169, v[84:87] offset:36864
	s_waitcnt vmcnt(18)
	ds_write_b128 v169, v[88:91] offset:45056
	s_waitcnt vmcnt(17)
	ds_write_b128 v169, v[92:95] offset:53248
	s_waitcnt vmcnt(16)
	ds_write_b128 v169, v[96:99] offset:61440
	s_waitcnt vmcnt(15)
	ds_write_b128 v170, v[100:103] offset:36864
	global_load_dwordx4 v[64:67], v164, s[98:99]
	global_load_dwordx4 v[68:71], v165, s[98:99]
	global_load_dwordx4 v[72:75], v166, s[98:99]
	global_load_dwordx4 v[76:79], v167, s[98:99]
	global_load_dwordx4 v[80:83], v168, s[96:97]
	s_add_u32 s98, s98, 0x100
	s_addc_u32 s99, s99, 0
	s_add_u32 s96, s96, 0x100
	s_addc_u32 s97, s97, 0
	ds_read_b128 v[204:207], v175
	ds_read_b128 v[208:211], v171
	ds_read_b128 v[212:215], v176
	ds_read_b128 v[216:219], v172
	ds_read_b128 v[220:223], v177
	ds_read_b128 v[224:227], v173
	ds_read_b128 v[228:231], v178
	ds_read_b128 v[232:235], v174
	s_waitcnt lgkmcnt(6)
	v_mfma_f32_16x16x32_bf16 v[0:3], v[204:207], v[208:211], v[0:3]
	s_waitcnt lgkmcnt(4)
	v_mfma_f32_16x16x32_bf16 v[0:3], v[212:215], v[216:219], v[0:3]
	s_waitcnt lgkmcnt(2)
	v_mfma_f32_16x16x32_bf16 v[0:3], v[220:223], v[224:227], v[0:3]
	s_waitcnt lgkmcnt(0)
	v_mfma_f32_16x16x32_bf16 v[0:3], v[228:231], v[232:235], v[0:3]
	s_waitcnt lgkmcnt(0)
	s_barrier
; template <int MODE>
; __device__ __forceinline__ void sgemm_sample(LAS unsigned char* lds, const bf16_t* A, const bf16_t* Bt, int K, const float* resid, float* out, bf16_t* xb, float* ssq_out, const float* ssq_in) {
;     ...
; #pragma unroll 8
;         for (int ks = 0; ks < K / 32; ++ks) {
;             const bf16x8 a = *(const bf16x8*)(ap + ks * 32); const bf16x8 b = *(const bf16x8*)(bp + ks * 32);
;             acc = __builtin_amdgcn_mfma_f32_16x16x32_bf16(b, a, acc, 0, 0, 0);
;         }
	s_waitcnt vmcnt(19)
	ds_write_b128 v169, v[104:107]
	s_waitcnt vmcnt(18)
	ds_write_b128 v169, v[108:111] offset:8192
	s_waitcnt vmcnt(17)
	ds_write_b128 v169, v[112:115] offset:16384
	s_waitcnt vmcnt(16)
	ds_write_b128 v169, v[116:119] offset:24576
	s_waitcnt vmcnt(15)
	ds_write_b128 v170, v[120:123]
	global_load_dwordx4 v[84:87], v164, s[98:99]
	global_load_dwordx4 v[88:91], v165, s[98:99]
	global_load_dwordx4 v[92:95], v166, s[98:99]
	global_load_dwordx4 v[96:99], v167, s[98:99]
	global_load_dwordx4 v[100:103], v168, s[96:97]
	s_add_u32 s98, s98, 0x100
	s_addc_u32 s99, s99, 0
	s_add_u32 s96, s96, 0x100
	s_addc_u32 s97, s97, 0
	ds_read_b128 v[204:207], v175 offset:36864
	ds_read_b128 v[208:211], v171 offset:36864
	ds_read_b128 v[212:215], v176 offset:36864
	ds_read_b128 v[216:219], v172 offset:36864
	ds_read_b128 v[220:223], v177 offset:36864
	ds_read_b128 v[224:227], v173 offset:36864
	ds_read_b128 v[228:231], v178 offset:36864
	ds_read_b128 v[232:235], v174 offset:36864
	s_waitcnt lgkmcnt(6)
	v_mfma_f32_16x16x32_bf16 v[0:3], v[204:207], v[208:211], v[0:3]
	s_waitcnt lgkmcnt(4)
	v_mfma_f32_16x16x32_bf16 v[0:3], v[212:215], v[216:219], v[0:3]
	s_waitcnt lgkmcnt(2)
	v_mfma_f32_16x16x32_bf16 v[0:3], v[220:223], v[224:227], v[0:3]
	s_waitcnt lgkmcnt(0)
	v_mfma_f32_16x16x32_bf16 v[0:3], v[228:231], v[232:235], v[0:3]
	s_waitcnt lgkmcnt(0)
	s_barrier
	s_waitcnt vmcnt(19)
	ds_write_b128 v169, v[124:127] offset:36864
	s_waitcnt vmcnt(18)
	ds_write_b128 v169, v[128:131] offset:45056
	s_waitcnt vmcnt(17)
	ds_write_b128 v169, v[132:135] offset:53248
	s_waitcnt vmcnt(16)
	ds_write_b128 v169, v[136:139] offset:61440
	s_waitcnt vmcnt(15)
	ds_write_b128 v170, v[140:143] offset:36864
	global_load_dwordx4 v[104:107], v164, s[98:99]
	global_load_dwordx4 v[108:111], v165, s[98:99]
	global_load_dwordx4 v[112:115], v166, s[98:99]
	global_load_dwordx4 v[116:119], v167, s[98:99]
	global_load_dwordx4 v[120:123], v168, s[96:97]
	s_add_u32 s98, s98, 0x100
	s_addc_u32 s99, s99, 0
	s_add_u32 s96, s96, 0x100
	s_addc_u32 s97, s97, 0
	ds_read_b128 v[204:207], v175
	ds_read_b128 v[208:211], v171
	ds_read_b128 v[212:215], v176
	ds_read_b128 v[216:219], v172
	ds_read_b128 v[220:223], v177
	ds_read_b128 v[224:227], v173
	ds_read_b128 v[228:231], v178
	ds_read_b128 v[232:235], v174
	s_waitcnt lgkmcnt(6)
	v_mfma_f32_16x16x32_bf16 v[0:3], v[204:207], v[208:211], v[0:3]
	s_waitcnt lgkmcnt(4)
	v_mfma_f32_16x16x32_bf16 v[0:3], v[212:215], v[216:219], v[0:3]
	s_waitcnt lgkmcnt(2)
	v_mfma_f32_16x16x32_bf16 v[0:3], v[220:223], v[224:227], v[0:3]
	s_waitcnt lgkmcnt(0)
	v_mfma_f32_16x16x32_bf16 v[0:3], v[228:231], v[232:235], v[0:3]
	s_waitcnt lgkmcnt(0)
	s_barrier
	s_waitcnt vmcnt(19)
	ds_write_b128 v169, v[144:147]
	s_waitcnt vmcnt(18)
	ds_write_b128 v169, v[148:151] offset:8192
	s_waitcnt vmcnt(17)
	ds_write_b128 v169, v[152:155] offset:16384
	s_waitcnt vmcnt(16)
	ds_write_b128 v169, v[156:159] offset:24576
	s_waitcnt vmcnt(15)
	ds_write_b128 v170, v[160:163]
	ds_read_b128 v[204:207], v175 offset:36864
	ds_read_b128 v[208:211], v171 offset:36864
	ds_read_b128 v[212:215], v176 offset:36864
	ds_read_b128 v[216:219], v172 offset:36864
	ds_read_b128 v[220:223], v177 offset:36864
	ds_read_b128 v[224:227], v173 offset:36864
	ds_read_b128 v[228:231], v178 offset:36864
	ds_read_b128 v[232:235], v174 offset:36864
	s_waitcnt lgkmcnt(6)
	v_mfma_f32_16x16x32_bf16 v[0:3], v[204:207], v[208:211], v[0:3]
	s_waitcnt lgkmcnt(4)
	v_mfma_f32_16x16x32_bf16 v[0:3], v[212:215], v[216:219], v[0:3]
	s_waitcnt lgkmcnt(2)
	v_mfma_f32_16x16x32_bf16 v[0:3], v[220:223], v[224:227], v[0:3]
	s_waitcnt lgkmcnt(0)
	v_mfma_f32_16x16x32_bf16 v[0:3], v[228:231], v[232:235], v[0:3]
	s_waitcnt lgkmcnt(0)
	s_barrier
; template <int MODE>
; __device__ __forceinline__ void sgemm_sample(LAS unsigned char* lds, const bf16_t* A, const bf16_t* Bt, int K, const float* resid, float* out, bf16_t* xb, float* ssq_out, const float* ssq_in) {
;     ...
; #pragma unroll 8
;         for (int ks = 0; ks < K / 32; ++ks) {
;             const bf16x8 a = *(const bf16x8*)(ap + ks * 32); const bf16x8 b = *(const bf16x8*)(bp + ks * 32);
;             acc = __builtin_amdgcn_mfma_f32_16x16x32_bf16(b, a, acc, 0, 0, 0);
;         }
	s_waitcnt vmcnt(14)
	ds_write_b128 v169, v[64:67] offset:36864
	s_waitcnt vmcnt(13)
	ds_write_b128 v169, v[68:71] offset:45056
	s_waitcnt vmcnt(12)
	ds_write_b128 v169, v[72:75] offset:53248
	s_waitcnt vmcnt(11)
	ds_write_b128 v169, v[76:79] offset:61440
	s_waitcnt vmcnt(10)
	ds_write_b128 v170, v[80:83] offset:36864
	ds_read_b128 v[204:207], v175
	ds_read_b128 v[208:211], v171
	ds_read_b128 v[212:215], v176
	ds_read_b128 v[216:219], v172
	ds_read_b128 v[220:223], v177
	ds_read_b128 v[224:227], v173
	ds_read_b128 v[228:231], v178
	ds_read_b128 v[232:235], v174
	s_waitcnt lgkmcnt(6)
	v_mfma_f32_16x16x32_bf16 v[0:3], v[204:207], v[208:211], v[0:3]
	s_waitcnt lgkmcnt(4)
	v_mfma_f32_16x16x32_bf16 v[0:3], v[212:215], v[216:219], v[0:3]
	s_waitcnt lgkmcnt(2)
	v_mfma_f32_16x16x32_bf16 v[0:3], v[220:223], v[224:227], v[0:3]
	s_waitcnt lgkmcnt(0)
	v_mfma_f32_16x16x32_bf16 v[0:3], v[228:231], v[232:235], v[0:3]
	s_waitcnt lgkmcnt(0)
	s_barrier
	s_waitcnt vmcnt(9)
	ds_write_b128 v169, v[84:87]
	s_waitcnt vmcnt(8)
	ds_write_b128 v169, v[88:91] offset:8192
	s_waitcnt vmcnt(7)
	ds_write_b128 v169, v[92:95] offset:16384
	s_waitcnt vmcnt(6)
	ds_write_b128 v169, v[96:99] offset:24576
	s_waitcnt vmcnt(5)
	ds_write_b128 v170, v[100:103]
	ds_read_b128 v[204:207], v175 offset:36864
	ds_read_b128 v[208:211], v171 offset:36864
	ds_read_b128 v[212:215], v176 offset:36864
	ds_read_b128 v[216:219], v172 offset:36864
	ds_read_b128 v[220:223], v177 offset:36864
	ds_read_b128 v[224:227], v173 offset:36864
	ds_read_b128 v[228:231], v178 offset:36864
	ds_read_b128 v[232:235], v174 offset:36864
	s_waitcnt lgkmcnt(6)
	v_mfma_f32_16x16x32_bf16 v[0:3], v[204:207], v[208:211], v[0:3]
	s_waitcnt lgkmcnt(4)
	v_mfma_f32_16x16x32_bf16 v[0:3], v[212:215], v[216:219], v[0:3]
	s_waitcnt lgkmcnt(2)
	v_mfma_f32_16x16x32_bf16 v[0:3], v[220:223], v[224:227], v[0:3]
	s_waitcnt lgkmcnt(0)
	v_mfma_f32_16x16x32_bf16 v[0:3], v[228:231], v[232:235], v[0:3]
	s_waitcnt lgkmcnt(0)
	s_barrier
	s_waitcnt vmcnt(4)
	ds_write_b128 v169, v[104:107] offset:36864
	s_waitcnt vmcnt(3)
	ds_write_b128 v169, v[108:111] offset:45056
	s_waitcnt vmcnt(2)
	ds_write_b128 v169, v[112:115] offset:53248
	s_waitcnt vmcnt(1)
	ds_write_b128 v169, v[116:119] offset:61440
	s_waitcnt vmcnt(0)
	ds_write_b128 v170, v[120:123] offset:36864
	ds_read_b128 v[204:207], v175
	ds_read_b128 v[208:211], v171
	ds_read_b128 v[212:215], v176
	ds_read_b128 v[216:219], v172
	ds_read_b128 v[220:223], v177
	ds_read_b128 v[224:227], v173
	ds_read_b128 v[228:231], v178
	ds_read_b128 v[232:235], v174
	s_waitcnt lgkmcnt(6)
	v_mfma_f32_16x16x32_bf16 v[0:3], v[204:207], v[208:211], v[0:3]
	s_waitcnt lgkmcnt(4)
	v_mfma_f32_16x16x32_bf16 v[0:3], v[212:215], v[216:219], v[0:3]
	s_waitcnt lgkmcnt(2)
	v_mfma_f32_16x16x32_bf16 v[0:3], v[220:223], v[224:227], v[0:3]
	s_waitcnt lgkmcnt(0)
	v_mfma_f32_16x16x32_bf16 v[0:3], v[228:231], v[232:235], v[0:3]
	s_waitcnt lgkmcnt(0)
	s_barrier
	ds_read_b128 v[204:207], v175 offset:36864
	ds_read_b128 v[208:211], v171 offset:36864
	ds_read_b128 v[212:215], v176 offset:36864
	ds_read_b128 v[216:219], v172 offset:36864
	ds_read_b128 v[220:223], v177 offset:36864
	ds_read_b128 v[224:227], v173 offset:36864
	ds_read_b128 v[228:231], v178 offset:36864
	ds_read_b128 v[232:235], v174 offset:36864
	s_waitcnt lgkmcnt(6)
	v_mfma_f32_16x16x32_bf16 v[0:3], v[204:207], v[208:211], v[0:3]
	s_waitcnt lgkmcnt(4)
	v_mfma_f32_16x16x32_bf16 v[0:3], v[212:215], v[216:219], v[0:3]
	s_waitcnt lgkmcnt(2)
	v_mfma_f32_16x16x32_bf16 v[0:3], v[220:223], v[224:227], v[0:3]
	s_waitcnt lgkmcnt(0)
	v_mfma_f32_16x16x32_bf16 v[0:3], v[228:231], v[232:235], v[0:3]
	s_nop 7
	s_branch .Lsgx1_done

; template <int MODE>
; __device__ __forceinline__ void sgemm_sample(LAS unsigned char* lds, const bf16_t* A, const bf16_t* Bt, int K, const float* resid, float* out, bf16_t* xb, float* ssq_out, const float* ssq_in) {
;     ...
;     for (int uu = u; uu < 2048; uu += gridDim.x * 8) {
;         const int rt = uu >> 6, ct = uu & 63; const int row = NTOKP + rt * 16 + fr, col0 = ct * 16 + fq * 4;
;         const bf16_t* ap = A + (size_t)row * K + fq * 8; const bf16_t* bp = Bt + (size_t)(ct * 16 + fr) * K + fq * 8;
;         f32x4 acc = {0.f, 0.f, 0.f, 0.f};
; #pragma unroll 8
;         for (int ks = 0; ks < K / 32; ++ks) {
;             const bf16x8 a = *(const bf16x8*)(ap + ks * 32); const bf16x8 b = *(const bf16x8*)(bp + ks * 32);
;             acc = __builtin_amdgcn_mfma_f32_16x16x32_bf16(b, a, acc, 0, 0, 0);
;         }
;     ...
;             const f32x4 x = *(const f32x4*)(resid + (size_t)(row - NTOKP) * D + col0) + acc;
.LBB0_1168:
	s_and_b32 s6, s15, 63
	v_lshl_or_b32 v4, s6, 15, v21
	s_ashr_i32 s6, s3, 2
	s_and_b32 s6, s6, -16
	s_add_i32 s6, s6, 0x8000
	v_or_b32_e32 v12, s6, v17
	v_ashrrev_i32_e32 v13, 31, v12
	v_lshlrev_b64 v[8:9], 11, v[12:13]
	v_lshl_add_u64 v[10:11], v[6:7], 0, v[4:5]
	v_lshl_add_u64 v[14:15], v[6:7], 0, v[8:9]
	s_mov_b64 s[18:19], 0
	v_mov_b32_e32 v0, 0
	v_mov_b32_e32 v1, v5
	v_mov_b32_e32 v2, v5
	v_mov_b32_e32 v3, v5
	s_cmpk_lg_i32 s34, 0x100
	s_cbranch_scc1 .LBB0_1169
	s_waitcnt vmcnt(0)
	s_and_b32 s20, s3, 63
	v_lshl_or_b32 v24, s20, 4, v18
	v_lshlrev_b64 v[14:15], 12, v[12:13]
	v_lshl_add_u64 v[10:11], s[10:11], 0, v[14:15]
	v_lshlrev_b32_e32 v4, 2, v24
	v_lshl_add_u64 v[10:11], v[10:11], 0, v[4:5]
	v_add_co_u32_e32 v10, vcc, 0xf8000000, v10
	v_lshl_add_u64 v[14:15], s[90:91], 0, v[14:15]
	s_nop 0
	v_addc_co_u32_e32 v11, vcc, -1, v11, vcc
	global_load_dwordx4 v[10:13], v[10:11], off
	s_lshr_b32 s100, s2, 3
	s_lshl_b32 s100, s100, 4
	s_add_i32 s100, s100, 0x8000
	s_mul_i32 s100, s100, 0x800
	s_add_u32 s96, s92, s100
	s_addc_u32 s97, s93, 0
	s_add_u32 s96, s96, 0x15780000
	s_addc_u32 s97, s97, 0
	s_and_b32 s100, s2, 7
	s_lshl_b32 s100, s100, 7
	s_mul_i32 s100, s100, 0x800
	s_add_u32 s98, s92, s100
	s_addc_u32 s99, s93, 0
	s_add_u32 s98, s98, 0x1040000
	s_addc_u32 s99, s99, 0
	v_lshrrev_b32_e32 v179, 4, v200
	v_and_b32_e32 v180, 15, v200
	v_and_b32_e32 v181, 15, v179
	v_xor_b32_e32 v180, v180, v181
	v_lshlrev_b32_e32 v180, 4, v180
	s_mov_b32 s100, 0x800
	v_mad_u32_u24 v164, v179, s100, v180
	v_add_u32_e32 v165, 0x10000, v164
	v_add_u32_e32 v166, 0x20000, v164
	v_add_u32_e32 v167, 0x30000, v164
	v_mad_u32_u24 v168, v181, s100, v180
	v_lshlrev_b32_e32 v169, 4, v200
	v_add_u32_e32 v169, 1024, v169
	v_and_b32_e32 v170, 0xff, v200
	v_lshlrev_b32_e32 v170, 4, v170
	v_add_u32_e32 v170, 33792, v170
	v_and_b32_e32 v179, 15, v200
	v_bfe_u32 v180, v200, 4, 2
	v_and_b32_e32 v181, 3, v179
	v_xor_b32_e32 v180, v180, v181
	v_lshlrev_b32_e32 v180, 4, v180
	v_lshrrev_b32_e32 v181, 2, v179
	v_lshl_add_u32 v180, v181, 6, v180
	v_lshl_add_u32 v180, v179, 8, v180
	v_add_u32_e32 v171, 33792, v180
	v_lshrrev_b32_e32 v181, 6, v200
	v_lshlrev_b32_e32 v181, 12, v181
	v_add_u32_e32 v175, v180, v181
	v_add_u32_e32 v175, 1024, v175
	v_xor_b32_e32 v172, 0x40, v171
	v_xor_b32_e32 v176, 0x40, v175
	v_xor_b32_e32 v173, 0x80, v171
	v_xor_b32_e32 v177, 0x80, v175
	v_xor_b32_e32 v174, 0xc0, v171
	v_xor_b32_e32 v178, 0xc0, v175
	global_load_dwordx4 v[64:67], v164, s[98:99]
	global_load_dwordx4 v[68:71], v165, s[98:99]
	global_load_dwordx4 v[72:75], v166, s[98:99]
	global_load_dwordx4 v[76:79], v167, s[98:99]
	global_load_dwordx4 v[80:83], v168, s[96:97]
	s_add_u32 s98, s98, 0x100
	s_addc_u32 s99, s99, 0
	s_add_u32 s96, s96, 0x100
	s_addc_u32 s97, s97, 0
	global_load_dwordx4 v[84:87], v164, s[98:99]
	global_load_dwordx4 v[88:91], v165, s[98:99]
	global_load_dwordx4 v[92:95], v166, s[98:99]
	global_load_dwordx4 v[96:99], v167, s[98:99]
	global_load_dwordx4 v[100:103], v168, s[96:97]
	s_add_u32 s98, s98, 0x100
	s_addc_u32 s99, s99, 0
	s_add_u32 s96, s96, 0x100
	s_addc_u32 s97, s97, 0
	global_load_dwordx4 v[104:107], v164, s[98:99]
	global_load_dwordx4 v[108:111], v165, s[98:99]
	global_load_dwordx4 v[112:115], v166, s[98:99]
	global_load_dwordx4 v[116:119], v167, s[98:99]
	global_load_dwordx4 v[120:123], v168, s[96:97]
	s_add_u32 s98, s98, 0x100
	s_addc_u32 s99, s99, 0
	s_add_u32 s96, s96, 0x100
	s_addc_u32 s97, s97, 0
	global_load_dwordx4 v[124:127], v164, s[98:99]
	global_load_dwordx4 v[128:131], v165, s[98:99]
	global_load_dwordx4 v[132:135], v166, s[98:99]
	global_load_dwordx4 v[136:139], v167, s[98:99]
	global_load_dwordx4 v[140:143], v168, s[96:97]
	s_add_u32 s98, s98, 0x100
	s_addc_u32 s99, s99, 0
	s_add_u32 s96, s96, 0x100
	s_addc_u32 s97, s97, 0
	global_load_dwordx4 v[144:147], v164, s[98:99]
	global_load_dwordx4 v[148:151], v165, s[98:99]
	global_load_dwordx4 v[152:155], v166, s[98:99]
	global_load_dwordx4 v[156:159], v167, s[98:99]
	global_load_dwordx4 v[160:163], v168, s[96:97]
	s_add_u32 s98, s98, 0x100
	s_addc_u32 s99, s99, 0
	s_add_u32 s96, s96, 0x100
	s_addc_u32 s97, s97, 0
	s_waitcnt vmcnt(24)
	ds_write_b128 v169, v[64:67]
	s_waitcnt vmcnt(23)
	ds_write_b128 v169, v[68:71] offset:8192
	s_waitcnt vmcnt(22)
	ds_write_b128 v169, v[72:75] offset:16384
	s_waitcnt vmcnt(21)
	ds_write_b128 v169, v[76:79] offset:24576
	s_waitcnt vmcnt(20)
	ds_write_b128 v170, v[80:83]
	s_waitcnt lgkmcnt(0)
	s_barrier
	s_waitcnt vmcnt(19)
	ds_write_b128 v169, v[84:87] offset:36864
	s_waitcnt vmcnt(18)
	ds_write_b128 v169, v[88:91] offset:45056
	s_waitcnt vmcnt(17)
	ds_write_b128 v169, v[92:95] offset:53248
	s_waitcnt vmcnt(16)
	ds_write_b128 v169, v[96:99] offset:61440
	s_waitcnt vmcnt(15)
	ds_write_b128 v170, v[100:103] offset:36864
	global_load_dwordx4 v[64:67], v164, s[98:99]
	global_load_dwordx4 v[68:71], v165, s[98:99]
	global_load_dwordx4 v[72:75], v166, s[98:99]
	global_load_dwordx4 v[76:79], v167, s[98:99]
	global_load_dwordx4 v[80:83], v168, s[96:97]
	s_add_u32 s98, s98, 0x100
	s_addc_u32 s99, s99, 0
	s_add_u32 s96, s96, 0x100
	s_addc_u32 s97, s97, 0
	ds_read_b128 v[204:207], v175
	ds_read_b128 v[208:211], v171
	ds_read_b128 v[212:215], v176
	ds_read_b128 v[216:219], v172
	ds_read_b128 v[220:223], v177
	ds_read_b128 v[224:227], v173
	ds_read_b128 v[228:231], v178
	ds_read_b128 v[232:235], v174
	s_waitcnt lgkmcnt(6)
	v_mfma_f32_16x16x32_bf16 v[0:3], v[204:207], v[208:211], v[0:3]
	s_waitcnt lgkmcnt(4)
	v_mfma_f32_16x16x32_bf16 v[0:3], v[212:215], v[216:219], v[0:3]
	s_waitcnt lgkmcnt(2)
	v_mfma_f32_16x16x32_bf16 v[0:3], v[220:223], v[224:227], v[0:3]
	s_waitcnt lgkmcnt(0)
	v_mfma_f32_16x16x32_bf16 v[0:3], v[228:231], v[232:235], v[0:3]
	s_waitcnt lgkmcnt(0)
	s_barrier
; template <int MODE>
; __device__ __forceinline__ void sgemm_sample(LAS unsigned char* lds, const bf16_t* A, const bf16_t* Bt, int K, const float* resid, float* out, bf16_t* xb, float* ssq_out, const float* ssq_in) {
;     ...
; #pragma unroll 8
;         for (int ks = 0; ks < K / 32; ++ks) {
;             const bf16x8 a = *(const bf16x8*)(ap + ks * 32); const bf16x8 b = *(const bf16x8*)(bp + ks * 32);
;             acc = __builtin_amdgcn_mfma_f32_16x16x32_bf16(b, a, acc, 0, 0, 0);
;         }
	s_waitcnt vmcnt(19)
	ds_write_b128 v169, v[104:107]
	s_waitcnt vmcnt(18)
	ds_write_b128 v169, v[108:111] offset:8192
	s_waitcnt vmcnt(17)
	ds_write_b128 v169, v[112:115] offset:16384
	s_waitcnt vmcnt(16)
	ds_write_b128 v169, v[116:119] offset:24576
	s_waitcnt vmcnt(15)
	ds_write_b128 v170, v[120:123]
	global_load_dwordx4 v[84:87], v164, s[98:99]
	global_load_dwordx4 v[88:91], v165, s[98:99]
	global_load_dwordx4 v[92:95], v166, s[98:99]
	global_load_dwordx4 v[96:99], v167, s[98:99]
	global_load_dwordx4 v[100:103], v168, s[96:97]
	s_add_u32 s98, s98, 0x100
	s_addc_u32 s99, s99, 0
	s_add_u32 s96, s96, 0x100
	s_addc_u32 s97, s97, 0
	ds_read_b128 v[204:207], v175 offset:36864
	ds_read_b128 v[208:211], v171 offset:36864
	ds_read_b128 v[212:215], v176 offset:36864
	ds_read_b128 v[216:219], v172 offset:36864
	ds_read_b128 v[220:223], v177 offset:36864
	ds_read_b128 v[224:227], v173 offset:36864
	ds_read_b128 v[228:231], v178 offset:36864
	ds_read_b128 v[232:235], v174 offset:36864
	s_waitcnt lgkmcnt(6)
	v_mfma_f32_16x16x32_bf16 v[0:3], v[204:207], v[208:211], v[0:3]
	s_waitcnt lgkmcnt(4)
	v_mfma_f32_16x16x32_bf16 v[0:3], v[212:215], v[216:219], v[0:3]
	s_waitcnt lgkmcnt(2)
	v_mfma_f32_16x16x32_bf16 v[0:3], v[220:223], v[224:227], v[0:3]
	s_waitcnt lgkmcnt(0)
	v_mfma_f32_16x16x32_bf16 v[0:3], v[228:231], v[232:235], v[0:3]
	s_waitcnt lgkmcnt(0)
	s_barrier
	s_waitcnt vmcnt(19)
	ds_write_b128 v169, v[124:127] offset:36864
	s_waitcnt vmcnt(18)
	ds_write_b128 v169, v[128:131] offset:45056
	s_waitcnt vmcnt(17)
	ds_write_b128 v169, v[132:135] offset:53248
	s_waitcnt vmcnt(16)
	ds_write_b128 v169, v[136:139] offset:61440
	s_waitcnt vmcnt(15)
	ds_write_b128 v170, v[140:143] offset:36864
	global_load_dwordx4 v[104:107], v164, s[98:99]
	global_load_dwordx4 v[108:111], v165, s[98:99]
	global_load_dwordx4 v[112:115], v166, s[98:99]
	global_load_dwordx4 v[116:119], v167, s[98:99]
	global_load_dwordx4 v[120:123], v168, s[96:97]
	s_add_u32 s98, s98, 0x100
	s_addc_u32 s99, s99, 0
	s_add_u32 s96, s96, 0x100
	s_addc_u32 s97, s97, 0
	ds_read_b128 v[204:207], v175
	ds_read_b128 v[208:211], v171
	ds_read_b128 v[212:215], v176
	ds_read_b128 v[216:219], v172
	ds_read_b128 v[220:223], v177
	ds_read_b128 v[224:227], v173
	ds_read_b128 v[228:231], v178
	ds_read_b128 v[232:235], v174
	s_waitcnt lgkmcnt(6)
	v_mfma_f32_16x16x32_bf16 v[0:3], v[204:207], v[208:211], v[0:3]
	s_waitcnt lgkmcnt(4)
	v_mfma_f32_16x16x32_bf16 v[0:3], v[212:215], v[216:219], v[0:3]
	s_waitcnt lgkmcnt(2)
	v_mfma_f32_16x16x32_bf16 v[0:3], v[220:223], v[224:227], v[0:3]
	s_waitcnt lgkmcnt(0)
	v_mfma_f32_16x16x32_bf16 v[0:3], v[228:231], v[232:235], v[0:3]
	s_waitcnt lgkmcnt(0)
	s_barrier
	s_waitcnt vmcnt(19)
	ds_write_b128 v169, v[144:147]
	s_waitcnt vmcnt(18)
	ds_write_b128 v169, v[148:151] offset:8192
	s_waitcnt vmcnt(17)
	ds_write_b128 v169, v[152:155] offset:16384
	s_waitcnt vmcnt(16)
	ds_write_b128 v169, v[156:159] offset:24576
	s_waitcnt vmcnt(15)
	ds_write_b128 v170, v[160:163]
	ds_read_b128 v[204:207], v175 offset:36864
	ds_read_b128 v[208:211], v171 offset:36864
	ds_read_b128 v[212:215], v176 offset:36864
	ds_read_b128 v[216:219], v172 offset:36864
	ds_read_b128 v[220:223], v177 offset:36864
	ds_read_b128 v[224:227], v173 offset:36864
	ds_read_b128 v[228:231], v178 offset:36864
	ds_read_b128 v[232:235], v174 offset:36864
	s_waitcnt lgkmcnt(6)
	v_mfma_f32_16x16x32_bf16 v[0:3], v[204:207], v[208:211], v[0:3]
	s_waitcnt lgkmcnt(4)
	v_mfma_f32_16x16x32_bf16 v[0:3], v[212:215], v[216:219], v[0:3]
	s_waitcnt lgkmcnt(2)
	v_mfma_f32_16x16x32_bf16 v[0:3], v[220:223], v[224:227], v[0:3]
	s_waitcnt lgkmcnt(0)
	v_mfma_f32_16x16x32_bf16 v[0:3], v[228:231], v[232:235], v[0:3]
	s_waitcnt lgkmcnt(0)
	s_barrier
; template <int MODE>
; __device__ __forceinline__ void sgemm_sample(LAS unsigned char* lds, const bf16_t* A, const bf16_t* Bt, int K, const float* resid, float* out, bf16_t* xb, float* ssq_out, const float* ssq_in) {
;     ...
; #pragma unroll 8
;         for (int ks = 0; ks < K / 32; ++ks) {
;             const bf16x8 a = *(const bf16x8*)(ap + ks * 32); const bf16x8 b = *(const bf16x8*)(bp + ks * 32);
;             acc = __builtin_amdgcn_mfma_f32_16x16x32_bf16(b, a, acc, 0, 0, 0);
;         }
	s_waitcnt vmcnt(14)
	ds_write_b128 v169, v[64:67] offset:36864
	s_waitcnt vmcnt(13)
	ds_write_b128 v169, v[68:71] offset:45056
	s_waitcnt vmcnt(12)
	ds_write_b128 v169, v[72:75] offset:53248
	s_waitcnt vmcnt(11)
	ds_write_b128 v169, v[76:79] offset:61440
	s_waitcnt vmcnt(10)
	ds_write_b128 v170, v[80:83] offset:36864
	ds_read_b128 v[204:207], v175
	ds_read_b128 v[208:211], v171
	ds_read_b128 v[212:215], v176
	ds_read_b128 v[216:219], v172
	ds_read_b128 v[220:223], v177
	ds_read_b128 v[224:227], v173
	ds_read_b128 v[228:231], v178
	ds_read_b128 v[232:235], v174
	s_waitcnt lgkmcnt(6)
	v_mfma_f32_16x16x32_bf16 v[0:3], v[204:207], v[208:211], v[0:3]
	s_waitcnt lgkmcnt(4)
	v_mfma_f32_16x16x32_bf16 v[0:3], v[212:215], v[216:219], v[0:3]
	s_waitcnt lgkmcnt(2)
	v_mfma_f32_16x16x32_bf16 v[0:3], v[220:223], v[224:227], v[0:3]
	s_waitcnt lgkmcnt(0)
	v_mfma_f32_16x16x32_bf16 v[0:3], v[228:231], v[232:235], v[0:3]
	s_waitcnt lgkmcnt(0)
	s_barrier
	s_waitcnt vmcnt(9)
	ds_write_b128 v169, v[84:87]
	s_waitcnt vmcnt(8)
	ds_write_b128 v169, v[88:91] offset:8192
	s_waitcnt vmcnt(7)
	ds_write_b128 v169, v[92:95] offset:16384
	s_waitcnt vmcnt(6)
	ds_write_b128 v169, v[96:99] offset:24576
	s_waitcnt vmcnt(5)
	ds_write_b128 v170, v[100:103]
	ds_read_b128 v[204:207], v175 offset:36864
	ds_read_b128 v[208:211], v171 offset:36864
	ds_read_b128 v[212:215], v176 offset:36864
	ds_read_b128 v[216:219], v172 offset:36864
	ds_read_b128 v[220:223], v177 offset:36864
	ds_read_b128 v[224:227], v173 offset:36864
	ds_read_b128 v[228:231], v178 offset:36864
	ds_read_b128 v[232:235], v174 offset:36864
	s_waitcnt lgkmcnt(6)
	v_mfma_f32_16x16x32_bf16 v[0:3], v[204:207], v[208:211], v[0:3]
	s_waitcnt lgkmcnt(4)
	v_mfma_f32_16x16x32_bf16 v[0:3], v[212:215], v[216:219], v[0:3]
	s_waitcnt lgkmcnt(2)
	v_mfma_f32_16x16x32_bf16 v[0:3], v[220:223], v[224:227], v[0:3]
	s_waitcnt lgkmcnt(0)
	v_mfma_f32_16x16x32_bf16 v[0:3], v[228:231], v[232:235], v[0:3]
	s_waitcnt lgkmcnt(0)
	s_barrier
	s_waitcnt vmcnt(4)
	ds_write_b128 v169, v[104:107] offset:36864
	s_waitcnt vmcnt(3)
	ds_write_b128 v169, v[108:111] offset:45056
	s_waitcnt vmcnt(2)
	ds_write_b128 v169, v[112:115] offset:53248
	s_waitcnt vmcnt(1)
	ds_write_b128 v169, v[116:119] offset:61440
	s_waitcnt vmcnt(0)
	ds_write_b128 v170, v[120:123] offset:36864
	ds_read_b128 v[204:207], v175
	ds_read_b128 v[208:211], v171
	ds_read_b128 v[212:215], v176
	ds_read_b128 v[216:219], v172
	ds_read_b128 v[220:223], v177
	ds_read_b128 v[224:227], v173
	ds_read_b128 v[228:231], v178
	ds_read_b128 v[232:235], v174
	s_waitcnt lgkmcnt(6)
	v_mfma_f32_16x16x32_bf16 v[0:3], v[204:207], v[208:211], v[0:3]
	s_waitcnt lgkmcnt(4)
	v_mfma_f32_16x16x32_bf16 v[0:3], v[212:215], v[216:219], v[0:3]
	s_waitcnt lgkmcnt(2)
	v_mfma_f32_16x16x32_bf16 v[0:3], v[220:223], v[224:227], v[0:3]
	s_waitcnt lgkmcnt(0)
	v_mfma_f32_16x16x32_bf16 v[0:3], v[228:231], v[232:235], v[0:3]
	s_waitcnt lgkmcnt(0)
	s_barrier
	ds_read_b128 v[204:207], v175 offset:36864
	ds_read_b128 v[208:211], v171 offset:36864
	ds_read_b128 v[212:215], v176 offset:36864
	ds_read_b128 v[216:219], v172 offset:36864
	ds_read_b128 v[220:223], v177 offset:36864
	ds_read_b128 v[224:227], v173 offset:36864
	ds_read_b128 v[228:231], v178 offset:36864
	ds_read_b128 v[232:235], v174 offset:36864
	s_waitcnt lgkmcnt(6)
	v_mfma_f32_16x16x32_bf16 v[0:3], v[204:207], v[208:211], v[0:3]
	s_waitcnt lgkmcnt(4)
	v_mfma_f32_16x16x32_bf16 v[0:3], v[212:215], v[216:219], v[0:3]
	s_waitcnt lgkmcnt(2)
	v_mfma_f32_16x16x32_bf16 v[0:3], v[220:223], v[224:227], v[0:3]
	s_waitcnt lgkmcnt(0)
	v_mfma_f32_16x16x32_bf16 v[0:3], v[228:231], v[232:235], v[0:3]
	s_nop 7
	s_branch .Lsgx2_done

; template <int MODE>
; __device__ __forceinline__ void sgemm_sample(LAS unsigned char* lds, const bf16_t* A, const bf16_t* Bt, int K, const float* resid, float* out, bf16_t* xb, float* ssq_out, const float* ssq_in) {
;     ...
;     for (int uu = u; uu < 2048; uu += gridDim.x * 8) {
;         const int rt = uu >> 6, ct = uu & 63; const int row = NTOKP + rt * 16 + fr, col0 = ct * 16 + fq * 4;
;         const bf16_t* ap = A + (size_t)row * K + fq * 8; const bf16_t* bp = Bt + (size_t)(ct * 16 + fr) * K + fq * 8;
;         f32x4 acc = {0.f, 0.f, 0.f, 0.f};
; #pragma unroll 8
;         for (int ks = 0; ks < K / 32; ++ks) {
;             const bf16x8 a = *(const bf16x8*)(ap + ks * 32); const bf16x8 b = *(const bf16x8*)(bp + ks * 32);
;             acc = __builtin_amdgcn_mfma_f32_16x16x32_bf16(b, a, acc, 0, 0, 0);
;         }
;         if (MODE == 0) {
;             const f32x4 x = *(const f32x4*)(resid + (size_t)(row - NTOKP) * D + col0) + acc;
.LBB0_1348:
	s_ashr_i32 s0, s3, 2
	s_and_b32 s0, s0, -16
	v_add_u32_e32 v8, s0, v16
	s_lshl_b32 s0, s3, 4
	s_and_b32 s10, s0, 0x3f0
	v_or_b32_e32 v0, s10, v14
	v_mul_u32_u24_e32 v0, 0xb00, v0
	v_mad_i64_i32 v[10:11], s[0:1], v8, s5, v[6:7]
	v_lshlrev_b32_e32 v4, 1, v0
	v_ashrrev_i32_e32 v9, 31, v8
	v_lshl_add_u64 v[12:13], v[6:7], 0, v[4:5]
	s_mov_b64 s[0:1], 0
	v_mov_b32_e32 v0, 0
	s_waitcnt lgkmcnt(0)
	v_mov_b32_e32 v1, v5
	v_mov_b32_e32 v2, v5
	v_mov_b32_e32 v3, v5
	s_cmpk_lg_i32 s34, 0x100
	s_cbranch_scc1 .LBB0_1349
	s_waitcnt vmcnt(0)
	v_or_b32_e32 v4, s10, v15
	v_lshlrev_b64 v[12:13], 12, v[8:9]
	v_lshl_add_u64 v[8:9], s[8:9], 0, v[12:13]
	v_lshlrev_b32_e32 v4, 2, v4
	v_lshl_add_u64 v[8:9], v[8:9], 0, v[4:5]
	v_add_co_u32_e32 v8, vcc, 0xf8000000, v8
	s_add_i32 s3, s3, s4
	s_nop 0
	v_addc_co_u32_e32 v9, vcc, -1, v9, vcc
	global_load_dwordx4 v[8:11], v[8:9], off
	s_lshr_b32 s100, s2, 3
	s_lshl_b32 s100, s100, 4
	s_add_i32 s100, s100, 0x8000
	s_mul_i32 s100, s100, 0x1600
	s_add_u32 s96, s92, s100
	s_addc_u32 s97, s93, 0
	s_add_u32 s96, s96, 0x22c0000
	s_addc_u32 s97, s97, 0
	s_and_b32 s100, s2, 7
	s_lshl_b32 s100, s100, 7
	s_mul_i32 s100, s100, 0x1600
	s_add_u32 s98, s92, s100
	s_addc_u32 s99, s93, 0
	s_add_u32 s98, s98, 0x1d40000
	s_addc_u32 s99, s99, 0
	v_lshrrev_b32_e32 v179, 4, v200
	v_and_b32_e32 v180, 15, v200
	v_and_b32_e32 v181, 15, v179
	v_xor_b32_e32 v180, v180, v181
	v_lshlrev_b32_e32 v180, 4, v180
	s_mov_b32 s100, 0x1600
	v_mad_u32_u24 v164, v179, s100, v180
	v_add_u32_e32 v165, 0x2c000, v164
	v_add_u32_e32 v166, 0x58000, v164
	v_add_u32_e32 v167, 0x84000, v164
	v_mad_u32_u24 v168, v181, s100, v180
	v_lshlrev_b32_e32 v169, 4, v200
	v_add_u32_e32 v169, 1024, v169
	v_and_b32_e32 v170, 0xff, v200
	v_lshlrev_b32_e32 v170, 4, v170
	v_add_u32_e32 v170, 33792, v170
	v_and_b32_e32 v179, 15, v200
	v_bfe_u32 v180, v200, 4, 2
	v_and_b32_e32 v181, 3, v179
	v_xor_b32_e32 v180, v180, v181
	v_lshlrev_b32_e32 v180, 4, v180
	v_lshrrev_b32_e32 v181, 2, v179
	v_lshl_add_u32 v180, v181, 6, v180
	v_lshl_add_u32 v180, v179, 8, v180
	v_add_u32_e32 v171, 33792, v180
	v_lshrrev_b32_e32 v181, 6, v200
	v_lshlrev_b32_e32 v181, 12, v181
	v_add_u32_e32 v175, v180, v181
	v_add_u32_e32 v175, 1024, v175
	v_xor_b32_e32 v172, 0x40, v171
	v_xor_b32_e32 v176, 0x40, v175
	v_xor_b32_e32 v173, 0x80, v171
	v_xor_b32_e32 v177, 0x80, v175
	v_xor_b32_e32 v174, 0xc0, v171
	v_xor_b32_e32 v178, 0xc0, v175
	global_load_dwordx4 v[64:67], v164, s[98:99]
	global_load_dwordx4 v[68:71], v165, s[98:99]
	global_load_dwordx4 v[72:75], v166, s[98:99]
	global_load_dwordx4 v[76:79], v167, s[98:99]
	global_load_dwordx4 v[80:83], v168, s[96:97]
	s_add_u32 s98, s98, 0x100
	s_addc_u32 s99, s99, 0
	s_add_u32 s96, s96, 0x100
	s_addc_u32 s97, s97, 0
	global_load_dwordx4 v[84:87], v164, s[98:99]
	global_load_dwordx4 v[88:91], v165, s[98:99]
	global_load_dwordx4 v[92:95], v166, s[98:99]
	global_load_dwordx4 v[96:99], v167, s[98:99]
	global_load_dwordx4 v[100:103], v168, s[96:97]
	s_add_u32 s98, s98, 0x100
	s_addc_u32 s99, s99, 0
	s_add_u32 s96, s96, 0x100
	s_addc_u32 s97, s97, 0
	global_load_dwordx4 v[104:107], v164, s[98:99]
	global_load_dwordx4 v[108:111], v165, s[98:99]
	global_load_dwordx4 v[112:115], v166, s[98:99]
	global_load_dwordx4 v[116:119], v167, s[98:99]
	global_load_dwordx4 v[120:123], v168, s[96:97]
	s_add_u32 s98, s98, 0x100
	s_addc_u32 s99, s99, 0
	s_add_u32 s96, s96, 0x100
	s_addc_u32 s97, s97, 0
	global_load_dwordx4 v[124:127], v164, s[98:99]
	global_load_dwordx4 v[128:131], v165, s[98:99]
	global_load_dwordx4 v[132:135], v166, s[98:99]
	global_load_dwordx4 v[136:139], v167, s[98:99]
	global_load_dwordx4 v[140:143], v168, s[96:97]
	s_add_u32 s98, s98, 0x100
	s_addc_u32 s99, s99, 0
	s_add_u32 s96, s96, 0x100
	s_addc_u32 s97, s97, 0
	global_load_dwordx4 v[144:147], v164, s[98:99]
	global_load_dwordx4 v[148:151], v165, s[98:99]
	global_load_dwordx4 v[152:155], v166, s[98:99]
	global_load_dwordx4 v[156:159], v167, s[98:99]
	global_load_dwordx4 v[160:163], v168, s[96:97]
	s_add_u32 s98, s98, 0x100
	s_addc_u32 s99, s99, 0
	s_add_u32 s96, s96, 0x100
	s_addc_u32 s97, s97, 0
	s_waitcnt vmcnt(24)
	ds_write_b128 v169, v[64:67]
	s_waitcnt vmcnt(23)
	ds_write_b128 v169, v[68:71] offset:8192
	s_waitcnt vmcnt(22)
	ds_write_b128 v169, v[72:75] offset:16384
	s_waitcnt vmcnt(21)
	ds_write_b128 v169, v[76:79] offset:24576
	s_waitcnt vmcnt(20)
	ds_write_b128 v170, v[80:83]
	s_waitcnt lgkmcnt(0)
	s_barrier
	s_waitcnt vmcnt(19)
	ds_write_b128 v169, v[84:87] offset:36864
	s_waitcnt vmcnt(18)
	ds_write_b128 v169, v[88:91] offset:45056
	s_waitcnt vmcnt(17)
	ds_write_b128 v169, v[92:95] offset:53248
	s_waitcnt vmcnt(16)
	ds_write_b128 v169, v[96:99] offset:61440
	s_waitcnt vmcnt(15)
	ds_write_b128 v170, v[100:103] offset:36864
	global_load_dwordx4 v[64:67], v164, s[98:99]
	global_load_dwordx4 v[68:71], v165, s[98:99]
	global_load_dwordx4 v[72:75], v166, s[98:99]
	global_load_dwordx4 v[76:79], v167, s[98:99]
	global_load_dwordx4 v[80:83], v168, s[96:97]
	s_add_u32 s98, s98, 0x100
	s_addc_u32 s99, s99, 0
	s_add_u32 s96, s96, 0x100
	s_addc_u32 s97, s97, 0
	ds_read_b128 v[204:207], v175
	ds_read_b128 v[208:211], v171
	ds_read_b128 v[212:215], v176
	ds_read_b128 v[216:219], v172
	ds_read_b128 v[220:223], v177
	ds_read_b128 v[224:227], v173
	ds_read_b128 v[228:231], v178
	ds_read_b128 v[232:235], v174
	s_waitcnt lgkmcnt(6)
	v_mfma_f32_16x16x32_bf16 v[0:3], v[204:207], v[208:211], v[0:3]
	s_waitcnt lgkmcnt(4)
	v_mfma_f32_16x16x32_bf16 v[0:3], v[212:215], v[216:219], v[0:3]
	s_waitcnt lgkmcnt(2)
	v_mfma_f32_16x16x32_bf16 v[0:3], v[220:223], v[224:227], v[0:3]
	s_waitcnt lgkmcnt(0)
	v_mfma_f32_16x16x32_bf16 v[0:3], v[228:231], v[232:235], v[0:3]
	s_waitcnt lgkmcnt(0)
	s_barrier
; template <int MODE>
; __device__ __forceinline__ void sgemm_sample(LAS unsigned char* lds, const bf16_t* A, const bf16_t* Bt, int K, const float* resid, float* out, bf16_t* xb, float* ssq_out, const float* ssq_in) {
;     ...
; #pragma unroll 8
;         for (int ks = 0; ks < K / 32; ++ks) {
;             const bf16x8 a = *(const bf16x8*)(ap + ks * 32); const bf16x8 b = *(const bf16x8*)(bp + ks * 32);
;             acc = __builtin_amdgcn_mfma_f32_16x16x32_bf16(b, a, acc, 0, 0, 0);
;         }
	s_waitcnt vmcnt(19)
	ds_write_b128 v169, v[104:107]
	s_waitcnt vmcnt(18)
	ds_write_b128 v169, v[108:111] offset:8192
	s_waitcnt vmcnt(17)
	ds_write_b128 v169, v[112:115] offset:16384
	s_waitcnt vmcnt(16)
	ds_write_b128 v169, v[116:119] offset:24576
	s_waitcnt vmcnt(15)
	ds_write_b128 v170, v[120:123]
	global_load_dwordx4 v[84:87], v164, s[98:99]
	global_load_dwordx4 v[88:91], v165, s[98:99]
	global_load_dwordx4 v[92:95], v166, s[98:99]
	global_load_dwordx4 v[96:99], v167, s[98:99]
	global_load_dwordx4 v[100:103], v168, s[96:97]
	s_add_u32 s98, s98, 0x100
	s_addc_u32 s99, s99, 0
	s_add_u32 s96, s96, 0x100
	s_addc_u32 s97, s97, 0
	ds_read_b128 v[204:207], v175 offset:36864
	ds_read_b128 v[208:211], v171 offset:36864
	ds_read_b128 v[212:215], v176 offset:36864
	ds_read_b128 v[216:219], v172 offset:36864
	ds_read_b128 v[220:223], v177 offset:36864
	ds_read_b128 v[224:227], v173 offset:36864
	ds_read_b128 v[228:231], v178 offset:36864
	ds_read_b128 v[232:235], v174 offset:36864
	s_waitcnt lgkmcnt(6)
	v_mfma_f32_16x16x32_bf16 v[0:3], v[204:207], v[208:211], v[0:3]
	s_waitcnt lgkmcnt(4)
	v_mfma_f32_16x16x32_bf16 v[0:3], v[212:215], v[216:219], v[0:3]
	s_waitcnt lgkmcnt(2)
	v_mfma_f32_16x16x32_bf16 v[0:3], v[220:223], v[224:227], v[0:3]
	s_waitcnt lgkmcnt(0)
	v_mfma_f32_16x16x32_bf16 v[0:3], v[228:231], v[232:235], v[0:3]
	s_waitcnt lgkmcnt(0)
	s_barrier
	s_waitcnt vmcnt(19)
	ds_write_b128 v169, v[124:127] offset:36864
	s_waitcnt vmcnt(18)
	ds_write_b128 v169, v[128:131] offset:45056
	s_waitcnt vmcnt(17)
	ds_write_b128 v169, v[132:135] offset:53248
	s_waitcnt vmcnt(16)
	ds_write_b128 v169, v[136:139] offset:61440
	s_waitcnt vmcnt(15)
	ds_write_b128 v170, v[140:143] offset:36864
	global_load_dwordx4 v[104:107], v164, s[98:99]
	global_load_dwordx4 v[108:111], v165, s[98:99]
	global_load_dwordx4 v[112:115], v166, s[98:99]
	global_load_dwordx4 v[116:119], v167, s[98:99]
	global_load_dwordx4 v[120:123], v168, s[96:97]
	s_add_u32 s98, s98, 0x100
	s_addc_u32 s99, s99, 0
	s_add_u32 s96, s96, 0x100
	s_addc_u32 s97, s97, 0
	ds_read_b128 v[204:207], v175
	ds_read_b128 v[208:211], v171
	ds_read_b128 v[212:215], v176
	ds_read_b128 v[216:219], v172
	ds_read_b128 v[220:223], v177
	ds_read_b128 v[224:227], v173
	ds_read_b128 v[228:231], v178
	ds_read_b128 v[232:235], v174
	s_waitcnt lgkmcnt(6)
	v_mfma_f32_16x16x32_bf16 v[0:3], v[204:207], v[208:211], v[0:3]
	s_waitcnt lgkmcnt(4)
	v_mfma_f32_16x16x32_bf16 v[0:3], v[212:215], v[216:219], v[0:3]
	s_waitcnt lgkmcnt(2)
	v_mfma_f32_16x16x32_bf16 v[0:3], v[220:223], v[224:227], v[0:3]
	s_waitcnt lgkmcnt(0)
	v_mfma_f32_16x16x32_bf16 v[0:3], v[228:231], v[232:235], v[0:3]
	s_waitcnt lgkmcnt(0)
	s_barrier
	s_waitcnt vmcnt(19)
	ds_write_b128 v169, v[144:147]
	s_waitcnt vmcnt(18)
	ds_write_b128 v169, v[148:151] offset:8192
	s_waitcnt vmcnt(17)
	ds_write_b128 v169, v[152:155] offset:16384
	s_waitcnt vmcnt(16)
	ds_write_b128 v169, v[156:159] offset:24576
	s_waitcnt vmcnt(15)
	ds_write_b128 v170, v[160:163]
	global_load_dwordx4 v[124:127], v164, s[98:99]
	global_load_dwordx4 v[128:131], v165, s[98:99]
	global_load_dwordx4 v[132:135], v166, s[98:99]
	global_load_dwordx4 v[136:139], v167, s[98:99]
	global_load_dwordx4 v[140:143], v168, s[96:97]
	s_add_u32 s98, s98, 0x100
	s_addc_u32 s99, s99, 0
	s_add_u32 s96, s96, 0x100
	s_addc_u32 s97, s97, 0
	ds_read_b128 v[204:207], v175 offset:36864
	ds_read_b128 v[208:211], v171 offset:36864
	ds_read_b128 v[212:215], v176 offset:36864
	ds_read_b128 v[216:219], v172 offset:36864
	ds_read_b128 v[220:223], v177 offset:36864
	ds_read_b128 v[224:227], v173 offset:36864
	ds_read_b128 v[228:231], v178 offset:36864
	ds_read_b128 v[232:235], v174 offset:36864
	s_waitcnt lgkmcnt(6)
	v_mfma_f32_16x16x32_bf16 v[0:3], v[204:207], v[208:211], v[0:3]
	s_waitcnt lgkmcnt(4)
	v_mfma_f32_16x16x32_bf16 v[0:3], v[212:215], v[216:219], v[0:3]
	s_waitcnt lgkmcnt(2)
	v_mfma_f32_16x16x32_bf16 v[0:3], v[220:223], v[224:227], v[0:3]
	s_waitcnt lgkmcnt(0)
	v_mfma_f32_16x16x32_bf16 v[0:3], v[228:231], v[232:235], v[0:3]
	s_waitcnt lgkmcnt(0)
	s_barrier
	s_waitcnt vmcnt(19)
	ds_write_b128 v169, v[64:67] offset:36864
	s_waitcnt vmcnt(18)
	ds_write_b128 v169, v[68:71] offset:45056
	s_waitcnt vmcnt(17)
	ds_write_b128 v169, v[72:75] offset:53248
	s_waitcnt vmcnt(16)
	ds_write_b128 v169, v[76:79] offset:61440
	s_waitcnt vmcnt(15)
	ds_write_b128 v170, v[80:83] offset:36864
	global_load_dwordx4 v[144:147], v164, s[98:99]
	global_load_dwordx4 v[148:151], v165, s[98:99]
	global_load_dwordx4 v[152:155], v166, s[98:99]
	global_load_dwordx4 v[156:159], v167, s[98:99]
	global_load_dwordx4 v[160:163], v168, s[96:97]
	s_add_u32 s98, s98, 0x100
	s_addc_u32 s99, s99, 0
	s_add_u32 s96, s96, 0x100
	s_addc_u32 s97, s97, 0
	ds_read_b128 v[204:207], v175
	ds_read_b128 v[208:211], v171
	ds_read_b128 v[212:215], v176
	ds_read_b128 v[216:219], v172
	ds_read_b128 v[220:223], v177
	ds_read_b128 v[224:227], v173
	ds_read_b128 v[228:231], v178
	ds_read_b128 v[232:235], v174
	s_waitcnt lgkmcnt(6)
	v_mfma_f32_16x16x32_bf16 v[0:3], v[204:207], v[208:211], v[0:3]
	s_waitcnt lgkmcnt(4)
	v_mfma_f32_16x16x32_bf16 v[0:3], v[212:215], v[216:219], v[0:3]
	s_waitcnt lgkmcnt(2)
	v_mfma_f32_16x16x32_bf16 v[0:3], v[220:223], v[224:227], v[0:3]
	s_waitcnt lgkmcnt(0)
	v_mfma_f32_16x16x32_bf16 v[0:3], v[228:231], v[232:235], v[0:3]
	s_waitcnt lgkmcnt(0)
	s_barrier
; template <int MODE>
; __device__ __forceinline__ void sgemm_sample(LAS unsigned char* lds, const bf16_t* A, const bf16_t* Bt, int K, const float* resid, float* out, bf16_t* xb, float* ssq_out, const float* ssq_in) {
;     ...
; #pragma unroll 8
;         for (int ks = 0; ks < K / 32; ++ks) {
;             const bf16x8 a = *(const bf16x8*)(ap + ks * 32); const bf16x8 b = *(const bf16x8*)(bp + ks * 32);
;             acc = __builtin_amdgcn_mfma_f32_16x16x32_bf16(b, a, acc, 0, 0, 0);
;         }
	s_waitcnt vmcnt(19)
	ds_write_b128 v169, v[84:87]
	s_waitcnt vmcnt(18)
	ds_write_b128 v169, v[88:91] offset:8192
	s_waitcnt vmcnt(17)
	ds_write_b128 v169, v[92:95] offset:16384
	s_waitcnt vmcnt(16)
	ds_write_b128 v169, v[96:99] offset:24576
	s_waitcnt vmcnt(15)
	ds_write_b128 v170, v[100:103]
	global_load_dwordx4 v[64:67], v164, s[98:99]
	global_load_dwordx4 v[68:71], v165, s[98:99]
	global_load_dwordx4 v[72:75], v166, s[98:99]
	global_load_dwordx4 v[76:79], v167, s[98:99]
	global_load_dwordx4 v[80:83], v168, s[96:97]
	s_add_u32 s98, s98, 0x100
	s_addc_u32 s99, s99, 0
	s_add_u32 s96, s96, 0x100
	s_addc_u32 s97, s97, 0
	ds_read_b128 v[204:207], v175 offset:36864
	ds_read_b128 v[208:211], v171 offset:36864
	ds_read_b128 v[212:215], v176 offset:36864
	ds_read_b128 v[216:219], v172 offset:36864
	ds_read_b128 v[220:223], v177 offset:36864
	ds_read_b128 v[224:227], v173 offset:36864
	ds_read_b128 v[228:231], v178 offset:36864
	ds_read_b128 v[232:235], v174 offset:36864
	s_waitcnt lgkmcnt(6)
	v_mfma_f32_16x16x32_bf16 v[0:3], v[204:207], v[208:211], v[0:3]
	s_waitcnt lgkmcnt(4)
	v_mfma_f32_16x16x32_bf16 v[0:3], v[212:215], v[216:219], v[0:3]
	s_waitcnt lgkmcnt(2)
	v_mfma_f32_16x16x32_bf16 v[0:3], v[220:223], v[224:227], v[0:3]
	s_waitcnt lgkmcnt(0)
	v_mfma_f32_16x16x32_bf16 v[0:3], v[228:231], v[232:235], v[0:3]
	s_waitcnt lgkmcnt(0)
	s_barrier
	s_waitcnt vmcnt(19)
	ds_write_b128 v169, v[104:107] offset:36864
	s_waitcnt vmcnt(18)
	ds_write_b128 v169, v[108:111] offset:45056
	s_waitcnt vmcnt(17)
	ds_write_b128 v169, v[112:115] offset:53248
	s_waitcnt vmcnt(16)
	ds_write_b128 v169, v[116:119] offset:61440
	s_waitcnt vmcnt(15)
	ds_write_b128 v170, v[120:123] offset:36864
	global_load_dwordx4 v[84:87], v164, s[98:99]
	global_load_dwordx4 v[88:91], v165, s[98:99]
	global_load_dwordx4 v[92:95], v166, s[98:99]
	global_load_dwordx4 v[96:99], v167, s[98:99]
	global_load_dwordx4 v[100:103], v168, s[96:97]
	s_add_u32 s98, s98, 0x100
	s_addc_u32 s99, s99, 0
	s_add_u32 s96, s96, 0x100
	s_addc_u32 s97, s97, 0
	ds_read_b128 v[204:207], v175
	ds_read_b128 v[208:211], v171
	ds_read_b128 v[212:215], v176
	ds_read_b128 v[216:219], v172
	ds_read_b128 v[220:223], v177
	ds_read_b128 v[224:227], v173
	ds_read_b128 v[228:231], v178
	ds_read_b128 v[232:235], v174
	s_waitcnt lgkmcnt(6)
	v_mfma_f32_16x16x32_bf16 v[0:3], v[204:207], v[208:211], v[0:3]
	s_waitcnt lgkmcnt(4)
	v_mfma_f32_16x16x32_bf16 v[0:3], v[212:215], v[216:219], v[0:3]
	s_waitcnt lgkmcnt(2)
	v_mfma_f32_16x16x32_bf16 v[0:3], v[220:223], v[224:227], v[0:3]
	s_waitcnt lgkmcnt(0)
	v_mfma_f32_16x16x32_bf16 v[0:3], v[228:231], v[232:235], v[0:3]
	s_waitcnt lgkmcnt(0)
	s_barrier
	s_waitcnt vmcnt(19)
	ds_write_b128 v169, v[124:127]
	s_waitcnt vmcnt(18)
	ds_write_b128 v169, v[128:131] offset:8192
	s_waitcnt vmcnt(17)
	ds_write_b128 v169, v[132:135] offset:16384
	s_waitcnt vmcnt(16)
	ds_write_b128 v169, v[136:139] offset:24576
	s_waitcnt vmcnt(15)
	ds_write_b128 v170, v[140:143]
	global_load_dwordx4 v[104:107], v164, s[98:99]
	global_load_dwordx4 v[108:111], v165, s[98:99]
	global_load_dwordx4 v[112:115], v166, s[98:99]
	global_load_dwordx4 v[116:119], v167, s[98:99]
	global_load_dwordx4 v[120:123], v168, s[96:97]
	s_add_u32 s98, s98, 0x100
	s_addc_u32 s99, s99, 0
	s_add_u32 s96, s96, 0x100
	s_addc_u32 s97, s97, 0
	ds_read_b128 v[204:207], v175 offset:36864
	ds_read_b128 v[208:211], v171 offset:36864
	ds_read_b128 v[212:215], v176 offset:36864
	ds_read_b128 v[216:219], v172 offset:36864
	ds_read_b128 v[220:223], v177 offset:36864
	ds_read_b128 v[224:227], v173 offset:36864
	ds_read_b128 v[228:231], v178 offset:36864
	ds_read_b128 v[232:235], v174 offset:36864
	s_waitcnt lgkmcnt(6)
	v_mfma_f32_16x16x32_bf16 v[0:3], v[204:207], v[208:211], v[0:3]
	s_waitcnt lgkmcnt(4)
	v_mfma_f32_16x16x32_bf16 v[0:3], v[212:215], v[216:219], v[0:3]
	s_waitcnt lgkmcnt(2)
	v_mfma_f32_16x16x32_bf16 v[0:3], v[220:223], v[224:227], v[0:3]
	s_waitcnt lgkmcnt(0)
	v_mfma_f32_16x16x32_bf16 v[0:3], v[228:231], v[232:235], v[0:3]
	s_waitcnt lgkmcnt(0)
	s_barrier
	s_waitcnt vmcnt(19)
	ds_write_b128 v169, v[144:147] offset:36864
	s_waitcnt vmcnt(18)
	ds_write_b128 v169, v[148:151] offset:45056
	s_waitcnt vmcnt(17)
	ds_write_b128 v169, v[152:155] offset:53248
	s_waitcnt vmcnt(16)
	ds_write_b128 v169, v[156:159] offset:61440
	s_waitcnt vmcnt(15)
	ds_write_b128 v170, v[160:163] offset:36864
	global_load_dwordx4 v[124:127], v164, s[98:99]
	global_load_dwordx4 v[128:131], v165, s[98:99]
	global_load_dwordx4 v[132:135], v166, s[98:99]
	global_load_dwordx4 v[136:139], v167, s[98:99]
	global_load_dwordx4 v[140:143], v168, s[96:97]
	s_add_u32 s98, s98, 0x100
	s_addc_u32 s99, s99, 0
	s_add_u32 s96, s96, 0x100
	s_addc_u32 s97, s97, 0
	ds_read_b128 v[204:207], v175
	ds_read_b128 v[208:211], v171
	ds_read_b128 v[212:215], v176
	ds_read_b128 v[216:219], v172
	ds_read_b128 v[220:223], v177
	ds_read_b128 v[224:227], v173
	ds_read_b128 v[228:231], v178
	ds_read_b128 v[232:235], v174
	s_waitcnt lgkmcnt(6)
	v_mfma_f32_16x16x32_bf16 v[0:3], v[204:207], v[208:211], v[0:3]
	s_waitcnt lgkmcnt(4)
	v_mfma_f32_16x16x32_bf16 v[0:3], v[212:215], v[216:219], v[0:3]
	s_waitcnt lgkmcnt(2)
	v_mfma_f32_16x16x32_bf16 v[0:3], v[220:223], v[224:227], v[0:3]
	s_waitcnt lgkmcnt(0)
	v_mfma_f32_16x16x32_bf16 v[0:3], v[228:231], v[232:235], v[0:3]
	s_waitcnt lgkmcnt(0)
	s_barrier
; template <int MODE>
; __device__ __forceinline__ void sgemm_sample(LAS unsigned char* lds, const bf16_t* A, const bf16_t* Bt, int K, const float* resid, float* out, bf16_t* xb, float* ssq_out, const float* ssq_in) {
;     ...
; #pragma unroll 8
;         for (int ks = 0; ks < K / 32; ++ks) {
;             const bf16x8 a = *(const bf16x8*)(ap + ks * 32); const bf16x8 b = *(const bf16x8*)(bp + ks * 32);
;             acc = __builtin_amdgcn_mfma_f32_16x16x32_bf16(b, a, acc, 0, 0, 0);
;         }
	s_waitcnt vmcnt(19)
	ds_write_b128 v169, v[64:67]
	s_waitcnt vmcnt(18)
	ds_write_b128 v169, v[68:71] offset:8192
	s_waitcnt vmcnt(17)
	ds_write_b128 v169, v[72:75] offset:16384
	s_waitcnt vmcnt(16)
	ds_write_b128 v169, v[76:79] offset:24576
	s_waitcnt vmcnt(15)
	ds_write_b128 v170, v[80:83]
	global_load_dwordx4 v[144:147], v164, s[98:99]
	global_load_dwordx4 v[148:151], v165, s[98:99]
	global_load_dwordx4 v[152:155], v166, s[98:99]
	global_load_dwordx4 v[156:159], v167, s[98:99]
	global_load_dwordx4 v[160:163], v168, s[96:97]
	s_add_u32 s98, s98, 0x100
	s_addc_u32 s99, s99, 0
	s_add_u32 s96, s96, 0x100
	s_addc_u32 s97, s97, 0
	ds_read_b128 v[204:207], v175 offset:36864
	ds_read_b128 v[208:211], v171 offset:36864
	ds_read_b128 v[212:215], v176 offset:36864
	ds_read_b128 v[216:219], v172 offset:36864
	ds_read_b128 v[220:223], v177 offset:36864
	ds_read_b128 v[224:227], v173 offset:36864
	ds_read_b128 v[228:231], v178 offset:36864
	ds_read_b128 v[232:235], v174 offset:36864
	s_waitcnt lgkmcnt(6)
	v_mfma_f32_16x16x32_bf16 v[0:3], v[204:207], v[208:211], v[0:3]
	s_waitcnt lgkmcnt(4)
	v_mfma_f32_16x16x32_bf16 v[0:3], v[212:215], v[216:219], v[0:3]
	s_waitcnt lgkmcnt(2)
	v_mfma_f32_16x16x32_bf16 v[0:3], v[220:223], v[224:227], v[0:3]
	s_waitcnt lgkmcnt(0)
	v_mfma_f32_16x16x32_bf16 v[0:3], v[228:231], v[232:235], v[0:3]
	s_waitcnt lgkmcnt(0)
	s_barrier
	s_waitcnt vmcnt(19)
	ds_write_b128 v169, v[84:87] offset:36864
	s_waitcnt vmcnt(18)
	ds_write_b128 v169, v[88:91] offset:45056
	s_waitcnt vmcnt(17)
	ds_write_b128 v169, v[92:95] offset:53248
	s_waitcnt vmcnt(16)
	ds_write_b128 v169, v[96:99] offset:61440
	s_waitcnt vmcnt(15)
	ds_write_b128 v170, v[100:103] offset:36864
	global_load_dwordx4 v[64:67], v164, s[98:99]
	global_load_dwordx4 v[68:71], v165, s[98:99]
	global_load_dwordx4 v[72:75], v166, s[98:99]
	global_load_dwordx4 v[76:79], v167, s[98:99]
	global_load_dwordx4 v[80:83], v168, s[96:97]
	s_add_u32 s98, s98, 0x100
	s_addc_u32 s99, s99, 0
	s_add_u32 s96, s96, 0x100
	s_addc_u32 s97, s97, 0
	ds_read_b128 v[204:207], v175
	ds_read_b128 v[208:211], v171
	ds_read_b128 v[212:215], v176
	ds_read_b128 v[216:219], v172
	ds_read_b128 v[220:223], v177
	ds_read_b128 v[224:227], v173
	ds_read_b128 v[228:231], v178
	ds_read_b128 v[232:235], v174
	s_waitcnt lgkmcnt(6)
	v_mfma_f32_16x16x32_bf16 v[0:3], v[204:207], v[208:211], v[0:3]
	s_waitcnt lgkmcnt(4)
	v_mfma_f32_16x16x32_bf16 v[0:3], v[212:215], v[216:219], v[0:3]
	s_waitcnt lgkmcnt(2)
	v_mfma_f32_16x16x32_bf16 v[0:3], v[220:223], v[224:227], v[0:3]
	s_waitcnt lgkmcnt(0)
	v_mfma_f32_16x16x32_bf16 v[0:3], v[228:231], v[232:235], v[0:3]
	s_waitcnt lgkmcnt(0)
	s_barrier
	s_waitcnt vmcnt(19)
	ds_write_b128 v169, v[104:107]
	s_waitcnt vmcnt(18)
	ds_write_b128 v169, v[108:111] offset:8192
	s_waitcnt vmcnt(17)
	ds_write_b128 v169, v[112:115] offset:16384
	s_waitcnt vmcnt(16)
	ds_write_b128 v169, v[116:119] offset:24576
	s_waitcnt vmcnt(15)
	ds_write_b128 v170, v[120:123]
	global_load_dwordx4 v[84:87], v164, s[98:99]
	global_load_dwordx4 v[88:91], v165, s[98:99]
	global_load_dwordx4 v[92:95], v166, s[98:99]
	global_load_dwordx4 v[96:99], v167, s[98:99]
	global_load_dwordx4 v[100:103], v168, s[96:97]
	s_add_u32 s98, s98, 0x100
	s_addc_u32 s99, s99, 0
	s_add_u32 s96, s96, 0x100
	s_addc_u32 s97, s97, 0
	ds_read_b128 v[204:207], v175 offset:36864
	ds_read_b128 v[208:211], v171 offset:36864
	ds_read_b128 v[212:215], v176 offset:36864
	ds_read_b128 v[216:219], v172 offset:36864
	ds_read_b128 v[220:223], v177 offset:36864
	ds_read_b128 v[224:227], v173 offset:36864
	ds_read_b128 v[228:231], v178 offset:36864
	ds_read_b128 v[232:235], v174 offset:36864
	s_waitcnt lgkmcnt(6)
	v_mfma_f32_16x16x32_bf16 v[0:3], v[204:207], v[208:211], v[0:3]
	s_waitcnt lgkmcnt(4)
	v_mfma_f32_16x16x32_bf16 v[0:3], v[212:215], v[216:219], v[0:3]
	s_waitcnt lgkmcnt(2)
	v_mfma_f32_16x16x32_bf16 v[0:3], v[220:223], v[224:227], v[0:3]
	s_waitcnt lgkmcnt(0)
	v_mfma_f32_16x16x32_bf16 v[0:3], v[228:231], v[232:235], v[0:3]
	s_waitcnt lgkmcnt(0)
	s_barrier
	s_waitcnt vmcnt(19)
	ds_write_b128 v169, v[124:127] offset:36864
	s_waitcnt vmcnt(18)
	ds_write_b128 v169, v[128:131] offset:45056
	s_waitcnt vmcnt(17)
	ds_write_b128 v169, v[132:135] offset:53248
	s_waitcnt vmcnt(16)
	ds_write_b128 v169, v[136:139] offset:61440
	s_waitcnt vmcnt(15)
	ds_write_b128 v170, v[140:143] offset:36864
	global_load_dwordx4 v[104:107], v164, s[98:99]
	global_load_dwordx4 v[108:111], v165, s[98:99]
	global_load_dwordx4 v[112:115], v166, s[98:99]
	global_load_dwordx4 v[116:119], v167, s[98:99]
	global_load_dwordx4 v[120:123], v168, s[96:97]
	s_add_u32 s98, s98, 0x100
	s_addc_u32 s99, s99, 0
	s_add_u32 s96, s96, 0x100
	s_addc_u32 s97, s97, 0
	ds_read_b128 v[204:207], v175
	ds_read_b128 v[208:211], v171
	ds_read_b128 v[212:215], v176
	ds_read_b128 v[216:219], v172
	ds_read_b128 v[220:223], v177
	ds_read_b128 v[224:227], v173
	ds_read_b128 v[228:231], v178
	ds_read_b128 v[232:235], v174
	s_waitcnt lgkmcnt(6)
	v_mfma_f32_16x16x32_bf16 v[0:3], v[204:207], v[208:211], v[0:3]
	s_waitcnt lgkmcnt(4)
	v_mfma_f32_16x16x32_bf16 v[0:3], v[212:215], v[216:219], v[0:3]
	s_waitcnt lgkmcnt(2)
	v_mfma_f32_16x16x32_bf16 v[0:3], v[220:223], v[224:227], v[0:3]
	s_waitcnt lgkmcnt(0)
	v_mfma_f32_16x16x32_bf16 v[0:3], v[228:231], v[232:235], v[0:3]
	s_waitcnt lgkmcnt(0)
	s_barrier
; template <int MODE>
; __device__ __forceinline__ void sgemm_sample(LAS unsigned char* lds, const bf16_t* A, const bf16_t* Bt, int K, const float* resid, float* out, bf16_t* xb, float* ssq_out, const float* ssq_in) {
;     ...
; #pragma unroll 8
;         for (int ks = 0; ks < K / 32; ++ks) {
;             const bf16x8 a = *(const bf16x8*)(ap + ks * 32); const bf16x8 b = *(const bf16x8*)(bp + ks * 32);
;             acc = __builtin_amdgcn_mfma_f32_16x16x32_bf16(b, a, acc, 0, 0, 0);
;         }
	s_waitcnt vmcnt(19)
	ds_write_b128 v169, v[144:147]
	s_waitcnt vmcnt(18)
	ds_write_b128 v169, v[148:151] offset:8192
	s_waitcnt vmcnt(17)
	ds_write_b128 v169, v[152:155] offset:16384
	s_waitcnt vmcnt(16)
	ds_write_b128 v169, v[156:159] offset:24576
	s_waitcnt vmcnt(15)
	ds_write_b128 v170, v[160:163]
	global_load_dwordx4 v[124:127], v164, s[98:99]
	global_load_dwordx4 v[128:131], v165, s[98:99]
	global_load_dwordx4 v[132:135], v166, s[98:99]
	global_load_dwordx4 v[136:139], v167, s[98:99]
	global_load_dwordx4 v[140:143], v168, s[96:97]
	s_add_u32 s98, s98, 0x100
	s_addc_u32 s99, s99, 0
	s_add_u32 s96, s96, 0x100
	s_addc_u32 s97, s97, 0
	ds_read_b128 v[204:207], v175 offset:36864
	ds_read_b128 v[208:211], v171 offset:36864
	ds_read_b128 v[212:215], v176 offset:36864
	ds_read_b128 v[216:219], v172 offset:36864
	ds_read_b128 v[220:223], v177 offset:36864
	ds_read_b128 v[224:227], v173 offset:36864
	ds_read_b128 v[228:231], v178 offset:36864
	ds_read_b128 v[232:235], v174 offset:36864
	s_waitcnt lgkmcnt(6)
	v_mfma_f32_16x16x32_bf16 v[0:3], v[204:207], v[208:211], v[0:3]
	s_waitcnt lgkmcnt(4)
	v_mfma_f32_16x16x32_bf16 v[0:3], v[212:215], v[216:219], v[0:3]
	s_waitcnt lgkmcnt(2)
	v_mfma_f32_16x16x32_bf16 v[0:3], v[220:223], v[224:227], v[0:3]
	s_waitcnt lgkmcnt(0)
	v_mfma_f32_16x16x32_bf16 v[0:3], v[228:231], v[232:235], v[0:3]
	s_waitcnt lgkmcnt(0)
	s_barrier
	s_waitcnt vmcnt(19)
	ds_write_b128 v169, v[64:67] offset:36864
	s_waitcnt vmcnt(18)
	ds_write_b128 v169, v[68:71] offset:45056
	s_waitcnt vmcnt(17)
	ds_write_b128 v169, v[72:75] offset:53248
	s_waitcnt vmcnt(16)
	ds_write_b128 v169, v[76:79] offset:61440
	s_waitcnt vmcnt(15)
	ds_write_b128 v170, v[80:83] offset:36864
	global_load_dwordx4 v[144:147], v164, s[98:99]
	global_load_dwordx4 v[148:151], v165, s[98:99]
	global_load_dwordx4 v[152:155], v166, s[98:99]
	global_load_dwordx4 v[156:159], v167, s[98:99]
	global_load_dwordx4 v[160:163], v168, s[96:97]
	s_add_u32 s98, s98, 0x100
	s_addc_u32 s99, s99, 0
	s_add_u32 s96, s96, 0x100
	s_addc_u32 s97, s97, 0
	ds_read_b128 v[204:207], v175
	ds_read_b128 v[208:211], v171
	ds_read_b128 v[212:215], v176
	ds_read_b128 v[216:219], v172
	ds_read_b128 v[220:223], v177
	ds_read_b128 v[224:227], v173
	ds_read_b128 v[228:231], v178
	ds_read_b128 v[232:235], v174
	s_waitcnt lgkmcnt(6)
	v_mfma_f32_16x16x32_bf16 v[0:3], v[204:207], v[208:211], v[0:3]
	s_waitcnt lgkmcnt(4)
	v_mfma_f32_16x16x32_bf16 v[0:3], v[212:215], v[216:219], v[0:3]
	s_waitcnt lgkmcnt(2)
	v_mfma_f32_16x16x32_bf16 v[0:3], v[220:223], v[224:227], v[0:3]
	s_waitcnt lgkmcnt(0)
	v_mfma_f32_16x16x32_bf16 v[0:3], v[228:231], v[232:235], v[0:3]
	s_waitcnt lgkmcnt(0)
	s_barrier
	s_waitcnt vmcnt(19)
	ds_write_b128 v169, v[84:87]
	s_waitcnt vmcnt(18)
	ds_write_b128 v169, v[88:91] offset:8192
	s_waitcnt vmcnt(17)
	ds_write_b128 v169, v[92:95] offset:16384
	s_waitcnt vmcnt(16)
	ds_write_b128 v169, v[96:99] offset:24576
	s_waitcnt vmcnt(15)
	ds_write_b128 v170, v[100:103]
	global_load_dwordx4 v[64:67], v164, s[98:99]
	global_load_dwordx4 v[68:71], v165, s[98:99]
	global_load_dwordx4 v[72:75], v166, s[98:99]
	global_load_dwordx4 v[76:79], v167, s[98:99]
	global_load_dwordx4 v[80:83], v168, s[96:97]
	s_add_u32 s98, s98, 0x100
	s_addc_u32 s99, s99, 0
	s_add_u32 s96, s96, 0x100
	s_addc_u32 s97, s97, 0
	ds_read_b128 v[204:207], v175 offset:36864
	ds_read_b128 v[208:211], v171 offset:36864
	ds_read_b128 v[212:215], v176 offset:36864
	ds_read_b128 v[216:219], v172 offset:36864
	ds_read_b128 v[220:223], v177 offset:36864
	ds_read_b128 v[224:227], v173 offset:36864
	ds_read_b128 v[228:231], v178 offset:36864
	ds_read_b128 v[232:235], v174 offset:36864
	s_waitcnt lgkmcnt(6)
	v_mfma_f32_16x16x32_bf16 v[0:3], v[204:207], v[208:211], v[0:3]
	s_waitcnt lgkmcnt(4)
	v_mfma_f32_16x16x32_bf16 v[0:3], v[212:215], v[216:219], v[0:3]
	s_waitcnt lgkmcnt(2)
	v_mfma_f32_16x16x32_bf16 v[0:3], v[220:223], v[224:227], v[0:3]
	s_waitcnt lgkmcnt(0)
	v_mfma_f32_16x16x32_bf16 v[0:3], v[228:231], v[232:235], v[0:3]
	s_waitcnt lgkmcnt(0)
	s_barrier
	s_waitcnt vmcnt(19)
	ds_write_b128 v169, v[104:107] offset:36864
	s_waitcnt vmcnt(18)
	ds_write_b128 v169, v[108:111] offset:45056
	s_waitcnt vmcnt(17)
	ds_write_b128 v169, v[112:115] offset:53248
	s_waitcnt vmcnt(16)
	ds_write_b128 v169, v[116:119] offset:61440
	s_waitcnt vmcnt(15)
	ds_write_b128 v170, v[120:123] offset:36864
	global_load_dwordx4 v[84:87], v164, s[98:99]
	global_load_dwordx4 v[88:91], v165, s[98:99]
	global_load_dwordx4 v[92:95], v166, s[98:99]
	global_load_dwordx4 v[96:99], v167, s[98:99]
	global_load_dwordx4 v[100:103], v168, s[96:97]
	s_add_u32 s98, s98, 0x100
	s_addc_u32 s99, s99, 0
	s_add_u32 s96, s96, 0x100
	s_addc_u32 s97, s97, 0
	ds_read_b128 v[204:207], v175
	ds_read_b128 v[208:211], v171
	ds_read_b128 v[212:215], v176
	ds_read_b128 v[216:219], v172
	ds_read_b128 v[220:223], v177
	ds_read_b128 v[224:227], v173
	ds_read_b128 v[228:231], v178
	ds_read_b128 v[232:235], v174
	s_waitcnt lgkmcnt(6)
	v_mfma_f32_16x16x32_bf16 v[0:3], v[204:207], v[208:211], v[0:3]
	s_waitcnt lgkmcnt(4)
	v_mfma_f32_16x16x32_bf16 v[0:3], v[212:215], v[216:219], v[0:3]
	s_waitcnt lgkmcnt(2)
	v_mfma_f32_16x16x32_bf16 v[0:3], v[220:223], v[224:227], v[0:3]
	s_waitcnt lgkmcnt(0)
	v_mfma_f32_16x16x32_bf16 v[0:3], v[228:231], v[232:235], v[0:3]
	s_waitcnt lgkmcnt(0)
	s_barrier
; template <int MODE>
; __device__ __forceinline__ void sgemm_sample(LAS unsigned char* lds, const bf16_t* A, const bf16_t* Bt, int K, const float* resid, float* out, bf16_t* xb, float* ssq_out, const float* ssq_in) {
;     ...
; #pragma unroll 8
;         for (int ks = 0; ks < K / 32; ++ks) {
;             const bf16x8 a = *(const bf16x8*)(ap + ks * 32); const bf16x8 b = *(const bf16x8*)(bp + ks * 32);
;             acc = __builtin_amdgcn_mfma_f32_16x16x32_bf16(b, a, acc, 0, 0, 0);
;         }
	s_waitcnt vmcnt(19)
	ds_write_b128 v169, v[124:127]
	s_waitcnt vmcnt(18)
	ds_write_b128 v169, v[128:131] offset:8192
	s_waitcnt vmcnt(17)
	ds_write_b128 v169, v[132:135] offset:16384
	s_waitcnt vmcnt(16)
	ds_write_b128 v169, v[136:139] offset:24576
	s_waitcnt vmcnt(15)
	ds_write_b128 v170, v[140:143]
	ds_read_b128 v[204:207], v175 offset:36864
	ds_read_b128 v[208:211], v171 offset:36864
	ds_read_b128 v[212:215], v176 offset:36864
	ds_read_b128 v[216:219], v172 offset:36864
	ds_read_b128 v[220:223], v177 offset:36864
	ds_read_b128 v[224:227], v173 offset:36864
	ds_read_b128 v[228:231], v178 offset:36864
	ds_read_b128 v[232:235], v174 offset:36864
	s_waitcnt lgkmcnt(6)
	v_mfma_f32_16x16x32_bf16 v[0:3], v[204:207], v[208:211], v[0:3]
	s_waitcnt lgkmcnt(4)
	v_mfma_f32_16x16x32_bf16 v[0:3], v[212:215], v[216:219], v[0:3]
	s_waitcnt lgkmcnt(2)
	v_mfma_f32_16x16x32_bf16 v[0:3], v[220:223], v[224:227], v[0:3]
	s_waitcnt lgkmcnt(0)
	v_mfma_f32_16x16x32_bf16 v[0:3], v[228:231], v[232:235], v[0:3]
	s_waitcnt lgkmcnt(0)
	s_barrier
	s_waitcnt vmcnt(14)
	ds_write_b128 v169, v[144:147] offset:36864
	s_waitcnt vmcnt(13)
	ds_write_b128 v169, v[148:151] offset:45056
	s_waitcnt vmcnt(12)
	ds_write_b128 v169, v[152:155] offset:53248
	s_waitcnt vmcnt(11)
	ds_write_b128 v169, v[156:159] offset:61440
	s_waitcnt vmcnt(10)
	ds_write_b128 v170, v[160:163] offset:36864
	ds_read_b128 v[204:207], v175
	ds_read_b128 v[208:211], v171
	ds_read_b128 v[212:215], v176
	ds_read_b128 v[216:219], v172
	ds_read_b128 v[220:223], v177
	ds_read_b128 v[224:227], v173
	ds_read_b128 v[228:231], v178
	ds_read_b128 v[232:235], v174
	s_waitcnt lgkmcnt(6)
	v_mfma_f32_16x16x32_bf16 v[0:3], v[204:207], v[208:211], v[0:3]
	s_waitcnt lgkmcnt(4)
	v_mfma_f32_16x16x32_bf16 v[0:3], v[212:215], v[216:219], v[0:3]
	s_waitcnt lgkmcnt(2)
	v_mfma_f32_16x16x32_bf16 v[0:3], v[220:223], v[224:227], v[0:3]
	s_waitcnt lgkmcnt(0)
	v_mfma_f32_16x16x32_bf16 v[0:3], v[228:231], v[232:235], v[0:3]
	s_waitcnt lgkmcnt(0)
	s_barrier
	s_waitcnt vmcnt(9)
	ds_write_b128 v169, v[64:67]
	s_waitcnt vmcnt(8)
	ds_write_b128 v169, v[68:71] offset:8192
	s_waitcnt vmcnt(7)
	ds_write_b128 v169, v[72:75] offset:16384
	s_waitcnt vmcnt(6)
	ds_write_b128 v169, v[76:79] offset:24576
	s_waitcnt vmcnt(5)
	ds_write_b128 v170, v[80:83]
	ds_read_b128 v[204:207], v175 offset:36864
	ds_read_b128 v[208:211], v171 offset:36864
	ds_read_b128 v[212:215], v176 offset:36864
	ds_read_b128 v[216:219], v172 offset:36864
	ds_read_b128 v[220:223], v177 offset:36864
	ds_read_b128 v[224:227], v173 offset:36864
	ds_read_b128 v[228:231], v178 offset:36864
	ds_read_b128 v[232:235], v174 offset:36864
	s_waitcnt lgkmcnt(6)
	v_mfma_f32_16x16x32_bf16 v[0:3], v[204:207], v[208:211], v[0:3]
	s_waitcnt lgkmcnt(4)
	v_mfma_f32_16x16x32_bf16 v[0:3], v[212:215], v[216:219], v[0:3]
	s_waitcnt lgkmcnt(2)
	v_mfma_f32_16x16x32_bf16 v[0:3], v[220:223], v[224:227], v[0:3]
	s_waitcnt lgkmcnt(0)
	v_mfma_f32_16x16x32_bf16 v[0:3], v[228:231], v[232:235], v[0:3]
	s_waitcnt lgkmcnt(0)
	s_barrier
	s_waitcnt vmcnt(4)
	ds_write_b128 v169, v[84:87] offset:36864
	s_waitcnt vmcnt(3)
	ds_write_b128 v169, v[88:91] offset:45056
	s_waitcnt vmcnt(2)
	ds_write_b128 v169, v[92:95] offset:53248
	s_waitcnt vmcnt(1)
	ds_write_b128 v169, v[96:99] offset:61440
	s_waitcnt vmcnt(0)
	ds_write_b128 v170, v[100:103] offset:36864
	ds_read_b128 v[204:207], v175
	ds_read_b128 v[208:211], v171
	ds_read_b128 v[212:215], v176
	ds_read_b128 v[216:219], v172
	ds_read_b128 v[220:223], v177
	ds_read_b128 v[224:227], v173
	ds_read_b128 v[228:231], v178
	ds_read_b128 v[232:235], v174
	s_waitcnt lgkmcnt(6)
	v_mfma_f32_16x16x32_bf16 v[0:3], v[204:207], v[208:211], v[0:3]
	s_waitcnt lgkmcnt(4)
	v_mfma_f32_16x16x32_bf16 v[0:3], v[212:215], v[216:219], v[0:3]
	s_waitcnt lgkmcnt(2)
	v_mfma_f32_16x16x32_bf16 v[0:3], v[220:223], v[224:227], v[0:3]
	s_waitcnt lgkmcnt(0)
	v_mfma_f32_16x16x32_bf16 v[0:3], v[228:231], v[232:235], v[0:3]
	s_waitcnt lgkmcnt(0)
	s_barrier
	ds_read_b128 v[204:207], v175 offset:36864
	ds_read_b128 v[208:211], v171 offset:36864
	ds_read_b128 v[212:215], v176 offset:36864
	ds_read_b128 v[216:219], v172 offset:36864
	ds_read_b128 v[220:223], v177 offset:36864
	ds_read_b128 v[224:227], v173 offset:36864
	ds_read_b128 v[228:231], v178 offset:36864
	ds_read_b128 v[232:235], v174 offset:36864
	s_waitcnt lgkmcnt(6)
	v_mfma_f32_16x16x32_bf16 v[0:3], v[204:207], v[208:211], v[0:3]
	s_waitcnt lgkmcnt(4)
	v_mfma_f32_16x16x32_bf16 v[0:3], v[212:215], v[216:219], v[0:3]
	s_waitcnt lgkmcnt(2)
	v_mfma_f32_16x16x32_bf16 v[0:3], v[220:223], v[224:227], v[0:3]
	s_waitcnt lgkmcnt(0)
	v_mfma_f32_16x16x32_bf16 v[0:3], v[228:231], v[232:235], v[0:3]
	s_nop 7
	s_branch .Lsgx3_done
